# layout change inside d_ws: SwiGLU hidden activations stored tile-blocked ([panel][k-tile][256 rows][64 cols]) and the two down-projection GEMM instances read their A operand from contiguous 32 KiB til
# speedup vs baseline: 1.0034x; 1.0034x over previous
; #define PG8_STAGE(bufoff, gbase, voff) do { _Pragma("unroll") for (int _i = 0; _i < 2; ++_i) \
;         __builtin_amdgcn_global_load_lds((const unsigned*)((const char*)(gbase) + (voff)[_i]), (PG8_LAS unsigned*)(lds + (bufoff) + ldsw + _i * 8192), 16, 0, 0); } while (0)
; #define PG8_BAR __builtin_amdgcn_s_barrier()
; template <class Epi, class Sched, bool ALIGN_EPI = false, bool SP2 = false>
; __device__ __forceinline__ void gemm_phase(PG8_LAS unsigned char* lds, const Gemm g, const Sched& S, const Epi& E) {
;     ...
;     for (int i = 0; i < 2; ++i) { int R, C; stage_rc(tid * 16 + i * 8192, R, C); const int Rb = Epi::PERM ? ((R & ~31) + perm32(R & 31)) : R;
;         voffA[i] = (unsigned)(R * K + C) * 2u; voffB[i] = (unsigned)(Rb * K + C) * 2u; }
;     const size_t kstep = (size_t)(BK * 2);
;     const size_t hstep = (size_t)HALF * K * 2;
;     const size_t tstep = 2 * hstep;
;     const unsigned ldsw = (unsigned)wid * 1024u;
;     const int aoff = lds_byte(wr * 64 + fr, fq * 8), boff = lds_byte(wc * 32 + fr, fq * 8);
;     ...
;     const char* cA = (const char*)g.A + (size_t)cur.pm * tstep; const char* cB = (const char*)g.Bt + (size_t)cur.pn * tstep;
;     S.a_ready(cur);
;     float epre[8];
;     if constexpr (Epi::PREFETCH) E.prefetch(cur, wr, fr, epre);
;     if constexpr (SP2) {
;         PG8_STAGE(PG8_SB(0, 0), cB, voffB); PG8_STAGE(PG8_SB(0, 1), cB + hstep, voffB); PG8_STAGE(PG8_SA(0, 0), cA, voffA); PG8_STAGE(PG8_SA(0, 1), cA + hstep, voffA);
;         if (wr == 1) PG8_BAR;
.LBB0_400:
	v_readlane_b32 s4, v253, 63
	v_readlane_b32 s5, v254, 0
	s_xor_b64 s[4:5], s[4:5], -1
	v_writelane_b32 v254, s4, 30
	s_lshr_b32 s85, s84, 6
	s_lshl_b32 s8, s84, 8
	v_writelane_b32 v254, s5, 31
	s_mov_b32 s9, s1
	s_andn2_b64 vcc, exec, s[2:3]
	s_lshl_b32 s86, s84, 9
	s_cbranch_vccnz .LBB0_434
	s_waitcnt lgkmcnt(1)
	v_bfe_i32 v2, v18, 27, 1
	v_lshlrev_b32_e32 v0, 4, v18
	v_lshrrev_b32_e32 v2, 22, v2
	v_add_u32_e32 v2, v0, v2
	v_and_b32_e32 v2, 0xfffffc00, v2
	v_sub_u32_e32 v2, v0, v2
	s_waitcnt lgkmcnt(0)
	v_ashrrev_i32_e32 v1, 31, v18
	s_waitcnt lgkmcnt(0)
	v_lshrrev_b32_e32 v3, 4, v2
	v_lshrrev_b32_e32 v1, 26, v1
	v_bitop3_b32 v2, v3, v2, 32 bitop3:0x6c
	v_add_u32_e32 v1, v18, v1
	v_ashrrev_i32_e32 v4, 31, v2
	v_ashrrev_i32_e32 v1, 6, v1
	v_lshrrev_b32_e32 v4, 26, v4
	v_lshlrev_b32_e32 v3, 3, v1
	v_add_u32_e32 v4, v2, v4
	v_and_b32_e32 v3, -16, v3
	v_ashrrev_i32_e32 v5, 6, v4
	v_lshlrev_b32_e32 v1, 5, v1
	v_add_u32_e32 v3, v5, v3
	v_and_b32_e32 v12, 32, v1
	v_and_b32_e32 v1, 0xc0, v4
	v_sub_u32_e32 v1, v2, v1
	v_lshlrev_b32_e32 v2, 1, v3
	v_lshrrev_b32_e32 v4, 2, v3
	v_and_b32_e32 v5, 3, v5
	s_mov_b32 s3, 0x7fffffe0
	v_ashrrev_i16_sdwa v1, v189, sext(v1) dst_sel:DWORD dst_unused:UNUSED_PAD src0_sel:DWORD src1_sel:BYTE_0
	v_and_b32_e32 v2, 24, v2
	v_and_b32_e32 v4, 4, v4
	v_and_or_b32 v5, v3, s3, v5
	v_bfe_i32 v13, v1, 0, 16
	v_or3_b32 v2, v5, v4, v2
	v_add_u32_e32 v1, v12, v13
	v_mul_lo_u32 v14, v3, s84
	v_mul_lo_u32 v2, v2, s84
	v_add_u32_e32 v0, 0x2000, v0
	v_add_lshl_u32 v130, v1, v14, 1
	v_add_lshl_u32 v132, v2, v1, 1
	v_ashrrev_i32_e32 v1, 31, v0
	v_lshrrev_b32_e32 v1, 22, v1
	v_add_u32_e32 v1, v0, v1
	v_ashrrev_i32_e32 v1, 10, v1
	v_mul_i32_i24_e32 v2, 0x400, v1
	v_sub_u32_e32 v0, v0, v2
	v_lshrrev_b32_e32 v2, 4, v0
	v_bitop3_b32 v0, v2, v0, 32 bitop3:0x6c
	v_ashrrev_i32_e32 v3, 31, v0
	v_lshrrev_b32_e32 v3, 26, v3
	v_lshlrev_b32_e32 v2, 3, v1
	v_add_u32_e32 v3, v0, v3
	v_and_b32_e32 v2, -16, v2
	v_ashrrev_i32_e32 v4, 6, v3
	s_ashr_i32 s2, s42, 6
	v_add_u32_e32 v2, v4, v2
	v_lshlrev_b32_e32 v1, 5, v1
	v_and_b32_e32 v4, 3, v4
	v_and_b32_e32 v15, 32, v1
	v_and_b32_e32 v1, 0xc0, v3
	v_and_or_b32 v4, v2, s3, v4
	s_ashr_i32 s3, s42, 8
	s_lshl_b32 s51, s2, 10
	s_mul_i32 s5, s86, s50
	v_readlane_b32 s40, v254, 28
	v_sub_u32_e32 v0, v0, v1
	v_lshlrev_b32_e32 v1, 1, v2
	v_lshrrev_b32_e32 v3, 2, v2
	s_mul_hi_i32 s4, s86, s50
	v_readlane_b32 s41, v254, 29
	s_add_u32 s44, s40, s5
	v_ashrrev_i16_sdwa v0, v189, sext(v0) dst_sel:DWORD dst_unused:UNUSED_PAD src0_sel:DWORD src1_sel:BYTE_0
	v_and_b32_e32 v1, 24, v1
	v_and_b32_e32 v3, 4, v3
	s_addc_u32 s45, s41, s4
	s_add_i32 s82, s51, 0
	v_bfe_i32 v16, v0, 0, 16
	v_or3_b32 v1, v4, v3, v1
	s_add_i32 m0, s82, 0x10000
	v_add_u32_e32 v0, v15, v16
	v_mul_lo_u32 v1, v1, s84
	global_load_lds_dwordx4 v132, s[44:45]
	s_add_i32 m0, s82, 0x12000
	v_add_lshl_u32 v136, v1, v0, 1
	s_add_u32 s4, s44, s8
	global_load_lds_dwordx4 v136, s[44:45]
	s_addc_u32 s5, s45, 0
	s_add_i32 m0, s82, 0x14000
	s_mul_i32 s39, s86, s0
	global_load_lds_dwordx4 v132, s[4:5]
	s_add_i32 m0, s82, 0x16000
	s_mul_hi_i32 s38, s86, s0
	s_add_u32 s46, s6, s39
	v_mov_b32_e32 v133, v32
	v_mov_b32_e32 v137, v32
	s_addc_u32 s47, s7, s38
	s_add_i32 s83, s82, 0x2000
	v_mul_lo_u32 v17, v2, s84
	v_lshl_add_u64 v[4:5], s[4:5], 0, v[132:133]
	v_lshl_add_u64 v[6:7], s[4:5], 0, v[136:137]
	global_load_lds_dwordx4 v136, s[4:5]
	s_mov_b32 m0, s82
	s_add_u32 s4, s46, 0x4000
	v_add_lshl_u32 v134, v0, v17, 1
	s_mov_b32 s100, 0x8000
	s_mov_b32 s101, 0
	v_and_b32_e32 v242, 63, v186
	v_lshlrev_b32_e32 v242, 4, v242
	v_lshrrev_b32_e32 v243, 4, v242
	v_and_b32_e32 v243, 32, v243
	v_xor_b32_e32 v242, v242, v243
	v_lshrrev_b32_e32 v243, 6, v242
	v_and_b32_e32 v242, 63, v242
	v_lshl_add_u32 v242, v243, 7, v242
	v_lshrrev_b32_e32 v243, 6, v186
	v_and_b32_e32 v244, 1, v243
	v_lshl_add_u32 v242, v244, 6, v242
	v_lshrrev_b32_e32 v243, 1, v243
	v_lshl_add_u32 v130, v243, 11, v242
	v_add_u32_e32 v134, 0x2000, v130
	global_load_lds_dwordx4 v130, s[46:47]
	s_mov_b32 m0, s83
	s_addc_u32 s5, s47, 0
	s_add_i32 s87, s82, 0x4000
	global_load_lds_dwordx4 v134, s[46:47]
	s_mov_b32 m0, s87
	s_add_i32 s88, s82, 0x6000
	global_load_lds_dwordx4 v130, s[4:5]
	s_mov_b32 m0, s88
	v_mov_b32_e32 v131, v32
	global_load_lds_dwordx4 v134, s[4:5]
	v_mov_b32_e32 v135, v32
	s_cmp_eq_u32 s3, 1
	v_lshl_add_u64 v[0:1], s[44:45], 0, v[132:133]
	v_lshl_add_u64 v[2:3], s[44:45], 0, v[136:137]
	v_lshl_add_u64 v[8:9], s[46:47], 0, v[130:131]
	v_lshl_add_u64 v[10:11], s[46:47], 0, v[134:135]
	s_cselect_b64 s[40:41], -1, 0
	s_cmp_lg_u32 s3, 1
	s_cbranch_scc1 .LBB0_403
	s_barrier
; #define PG8_STAGE(bufoff, gbase, voff) do { _Pragma("unroll") for (int _i = 0; _i < 2; ++_i) \
;         __builtin_amdgcn_global_load_lds((const unsigned*)((const char*)(gbase) + (voff)[_i]), (PG8_LAS unsigned*)(lds + (bufoff) + ldsw + _i * 8192), 16, 0, 0); } while (0)
; #define PG8_WAIT_V(n) asm volatile("s_waitcnt vmcnt(" #n ")" ::: "memory")
; #define PG8_BAR __builtin_amdgcn_s_barrier()
;     __host__ __device__ bool next(int i, Unit& u) const {
;         if (i >= ni) return false;
;         const long L = (long)(i + i0) * G + c; if (L >= nwg) return false;
;         int wgid = (int)L; { const int q = nwg / NXCD, r = nwg % NXCD, xcd = wgid % NXCD, off = wgid / NXCD; wgid = (xcd < r ? xcd * (q + 1) : r * (q + 1) + (xcd - r) * q) + off; }
;         const int nig = WGM * nN, gid = wgid / nig, fm = gid * WGM, gsz = (nM - fm) < WGM ? (nM - fm) : WGM;
;         u.pm = fm + ((wgid % nig) % gsz); u.pn = (wgid % nig) / gsz; return true;
; template <class Epi, class Sched, bool ALIGN_EPI = false, bool SP2 = false>
; __device__ __forceinline__ void gemm_phase(PG8_LAS unsigned char* lds, const Gemm g, const Sched& S, const Epi& E) {
;     ...
;         PG8_WAIT_V(2); PG8_BAR;
;         PG8_STAGE(PG8_SB(1, 0), cB + kstep, voffB); PG8_STAGE(PG8_SA(1, 0), cA + kstep, voffA); PG8_STAGE(PG8_SB(1, 1), cB + hstep + kstep, voffB);
;         PG8_WAIT_V(6); PG8_BAR;
;     } else {
;         PG8_STAGE(PG8_SB(0, 0), cB, voffB); PG8_STAGE(PG8_SA(0, 0), cA, voffA); PG8_STAGE(PG8_SB(0, 1), cB + hstep, voffB); PG8_STAGE(PG8_SA(0, 1), cA + hstep, voffA);
;         if (wr == 1) PG8_BAR;
;         PG8_WAIT_V(4); PG8_BAR;
;         PG8_STAGE(PG8_SB(1, 0), cB + kstep, voffB); PG8_STAGE(PG8_SA(1, 0), cA + kstep, voffA); PG8_STAGE(PG8_SB(1, 1), cB + hstep + kstep, voffB);
;         PG8_WAIT_V(6); PG8_BAR;
;     }
;     for (;;) {
;         const bool has_next = S.next(ui + 1, nxt);
;         const char* nA = has_next ? (const char*)g.A + (size_t)nxt.pm * tstep : cA; const char* nB = has_next ? (const char*)g.Bt + (size_t)nxt.pn * tstep : cB;
.LBB0_403:
	s_add_i32 m0, s82, 0x18000
	v_lshl_add_u64 v[0:1], v[0:1], 0, s[34:35]
	s_waitcnt vmcnt(2)
	s_barrier
	global_load_lds_dwordx4 v[0:1], off
	v_lshl_add_u64 v[0:1], v[2:3], 0, s[34:35]
	s_add_i32 m0, s82, 0x1a000
	s_add_i32 s90, s82, 0x8000
	global_load_lds_dwordx4 v[0:1], off
	v_lshl_add_u64 v[0:1], v[8:9], 0, s[100:101]
	s_mov_b32 m0, s90
	s_add_i32 s91, s82, 0xa000
	global_load_lds_dwordx4 v[0:1], off
	v_lshl_add_u64 v[0:1], v[10:11], 0, s[100:101]
	s_mov_b32 m0, s91
	v_bfe_u32 v19, v18, 4, 2
	global_load_lds_dwordx4 v[0:1], off
	s_add_i32 m0, s82, 0x1c000
	v_lshl_add_u64 v[0:1], v[4:5], 0, s[34:35]
	global_load_lds_dwordx4 v[0:1], off
	v_lshl_add_u64 v[0:1], v[6:7], 0, s[34:35]
	s_add_i32 m0, s82, 0x1e000
	v_and_b32_e32 v20, 15, v18
	global_load_lds_dwordx4 v[0:1], off
	v_lshlrev_b32_e32 v22, 4, v19
	v_lshlrev_b32_e32 v18, 2, v18
	s_and_b32 s89, s2, 3
	v_lshl_or_b32 v33, s3, 6, v20
	v_lshl_or_b32 v20, v20, 6, v22
	s_lshl_b32 s2, s3, 13
	v_and_b32_e32 v18, 32, v18
	v_bitop3_b32 v22, v20, s2, v18 bitop3:0xde
	s_lshl_b32 s2, s89, 12
	s_add_i32 s92, s85, -2
	s_cmpk_lt_u32 s42, 0x100
	s_cselect_b64 s[42:43], -1, 0
	s_cmpk_lt_i32 s53, 0x300
	s_cselect_b64 s[76:77], -1, 0
	s_add_i32 s4, s53, 0x100
	s_ashr_i32 s5, s4, 31
	s_lshr_b32 s5, s5, 29
	s_add_i32 s5, s4, s5
	s_ashr_i32 s38, s5, 3
	s_and_b32 s5, s5, -8
	s_sub_i32 s4, s4, s5
	s_lshl_b32 s5, s4, 7
	s_cmp_lt_i32 s4, 0
	s_mulk_i32 s4, 0x81
	s_cselect_b32 s4, s4, s5
	s_add_i32 s4, s4, s38
	s_ashr_i32 s5, s4, 31
	s_lshr_b32 s5, s5, 27
	s_add_i32 s5, s4, s5
	s_ashr_i32 s38, s5, 5
	s_and_b32 s5, s5, 0xffe0
	s_sub_i32 s4, s4, s5
	s_bfe_i32 s5, s4, 0x80000
	s_bfe_u32 s5, s5, 0x3000c
	s_add_i32 s5, s4, s5
	s_lshl_b32 s94, s38, 3
	s_and_b32 s38, s5, 0xf8
	s_sub_i32 s4, s4, s38
	v_add_u32_e32 v0, v17, v15
	s_sext_i32_i8 s4, s4
	v_add_lshl_u32 v0, v0, v16, 1
	v_mov_b32_e32 v1, v32
	s_waitcnt vmcnt(6)
	s_add_i32 s94, s94, s4
	s_bfe_i32 s4, s5, 0x80000
	v_lshl_add_u64 v[138:139], s[8:9], 0, v[0:1]
	v_add_u32_e32 v0, v14, v12
	v_lshlrev_b32_e32 v21, 3, v19
	s_sext_i32_i16 s4, s4
	v_add_lshl_u32 v0, v0, v13, 1
	v_bitop3_b32 v146, v20, s2, v18 bitop3:0xde
	v_lshl_or_b32 v147, s89, 5, v21
	s_mov_b32 s93, 0
	v_cmp_eq_u32_e64 s[2:3], 0, v19
	s_ashr_i32 s95, s4, 3
	v_lshl_add_u64 v[140:141], s[8:9], 0, v[0:1]
	v_add_u32_e32 v140, 0x4000, v130
	v_mov_b32_e32 v141, v32
	v_add_u32_e32 v138, 0x4000, v134
	v_mov_b32_e32 v139, v32
	v_add_u32_e32 v148, 0, v22
	s_mov_b64 s[78:79], s[46:47]
	s_barrier
	s_branch .LBB0_406

; #define PG8_STAGE(bufoff, gbase, voff) do { _Pragma("unroll") for (int _i = 0; _i < 2; ++_i) \
;         __builtin_amdgcn_global_load_lds((const unsigned*)((const char*)(gbase) + (voff)[_i]), (PG8_LAS unsigned*)(lds + (bufoff) + ldsw + _i * 8192), 16, 0, 0); } while (0)
; #define PG8_LDA(dst, b, h) do { _Pragma("unroll") for (int m = 0; m < 4; ++m) _Pragma("unroll") for (int k = 0; k < 2; ++k) dst[m][k] = *(const PG8_LAS bf16x8*)(lds + PG8_SA(b, h) + aoff + m * 2048 + k * 1024); } while (0)
; #define PG8_LDB(dst, b, h) do { _Pragma("unroll") for (int n = 0; n < 2; ++n) _Pragma("unroll") for (int k = 0; k < 2; ++k) dst[n][k] = *(const PG8_LAS bf16x8*)(lds + PG8_SB(b, h) + boff + n * 2048 + k * 1024); } while (0)
; #define PG8_MMA(ai, bj, At, Bt) do { __builtin_amdgcn_s_setprio(1); _Pragma("unroll") for (int m = 0; m < 4; ++m) _Pragma("unroll") for (int n = 0; n < 2; ++n) _Pragma("unroll") for (int k = 0; k < 2; ++k) \
;         acc[ai][bj][m][n] = __builtin_amdgcn_mfma_f32_16x16x32_bf16(Bt[n][k], At[m][k], acc[ai][bj][m][n], 0, 0, 0); __builtin_amdgcn_s_setprio(0); } while (0)
; #define PG8_WAIT_V(n) asm volatile("s_waitcnt vmcnt(" #n ")" ::: "memory")
; template <class Epi, class Sched, bool ALIGN_EPI = false, bool SP2 = false>
; __device__ __forceinline__ void gemm_phase(PG8_LAS unsigned char* lds, const Gemm g, const Sched& S, const Epi& E) {
;     ...
;         for (int t = 0; t < nt; t += 2) {
;             const bool last = (t == nt - 2);
;             const char* a1 = cA + (size_t)(t + 1) * kstep;
;             const char* a2 = last ? nA : cA + (size_t)(t + 2) * kstep; const char* b2 = last ? nB : cB + (size_t)(t + 2) * kstep;
;             const char* a3 = a2 + kstep; const char* b3 = b2 + kstep;
;             if (last && has_next) S.a_ready(nxt);
;             if constexpr (SP2) {
;             PG8_LDB(B0, 0, 0); PG8_LDB(B1, 0, 1); PG8_SCHED; PG8_LDA(At, 0, 0); PG8_STAGE(PG8_SA(1, 1), a1 + hstep, voffA);
;             PG8_WAIT_V(8); PG8_WAIT_L(0); PG8_BAR; PG8_MMA(0, 0, At, B0); PG8_MMA(0, 1, At, B1); PG8_BAR; PG8_SCHED;
;     ...
; #pragma unroll
;         for (int a = 0; a < 2; ++a)
; #pragma unroll
;             for (int b = 0; b < 2; ++b)
; #pragma unroll
;                 for (int m = 0; m < 4; ++m)
; #pragma unroll
;                     for (int n = 0; n < 2; ++n) acc[a][b][m][n] = (f32x4){0.f, 0.f, 0.f, 0.f};
;         cur = nxt; cA = nA; cB = nB; ++ui;
.LBB0_410:
	s_add_u32 s48, s44, 0x100
	s_addc_u32 s49, s45, 0
	s_add_u32 s44, s46, 0x8000
	v_mov_b32_e32 v0, 0
	s_addc_u32 s45, s47, 0
	s_mov_b32 s46, 0
	v_mov_b32_e32 v1, v0
	v_mov_b32_e32 v2, v0
	v_mov_b32_e32 v3, v0
	v_mov_b32_e32 v4, v0
	s_waitcnt lgkmcnt(0)
	v_mov_b32_e32 v5, v0
	v_mov_b32_e32 v6, v0
	v_mov_b32_e32 v7, v0
	v_mov_b32_e32 v16, v0
	v_mov_b32_e32 v17, v0
	v_mov_b32_e32 v18, v0
	v_mov_b32_e32 v19, v0
	v_mov_b32_e32 v20, v0
	v_mov_b32_e32 v21, v0
	v_mov_b32_e32 v22, v0
	v_mov_b32_e32 v23, v0
	v_mov_b32_e32 v34, v0
	v_mov_b32_e32 v35, v0
	v_mov_b32_e32 v36, v0
	v_mov_b32_e32 v37, v0
	v_mov_b32_e32 v38, v0
	v_mov_b32_e32 v39, v0
	v_mov_b32_e32 v40, v0
	v_mov_b32_e32 v41, v0
	v_mov_b32_e32 v50, v0
	v_mov_b32_e32 v51, v0
	v_mov_b32_e32 v52, v0
	v_mov_b32_e32 v53, v0
	v_mov_b32_e32 v54, v0
	v_mov_b32_e32 v55, v0
	v_mov_b32_e32 v56, v0
	v_mov_b32_e32 v57, v0
	v_mov_b32_e32 v8, v0
	v_mov_b32_e32 v9, v0
	v_mov_b32_e32 v10, v0
	v_mov_b32_e32 v11, v0
	v_mov_b32_e32 v12, v0
	v_mov_b32_e32 v13, v0
	v_mov_b32_e32 v14, v0
	v_mov_b32_e32 v15, v0
	v_mov_b32_e32 v24, v0
	v_mov_b32_e32 v25, v0
	v_mov_b32_e32 v26, v0
	v_mov_b32_e32 v27, v0
	v_mov_b32_e32 v28, v0
	v_mov_b32_e32 v29, v0
	v_mov_b32_e32 v30, v0
	v_mov_b32_e32 v31, v0
	v_mov_b32_e32 v42, v0
	v_mov_b32_e32 v43, v0
	v_mov_b32_e32 v44, v0
	v_mov_b32_e32 v45, v0
	v_mov_b32_e32 v46, v0
	v_mov_b32_e32 v47, v0
	v_mov_b32_e32 v48, v0
	v_mov_b32_e32 v49, v0
	v_mov_b32_e32 v58, v0
	v_mov_b32_e32 v59, v0
	v_mov_b32_e32 v60, v0
	v_mov_b32_e32 v61, v0
	v_mov_b32_e32 v62, v0
	v_mov_b32_e32 v63, v0
	v_mov_b32_e32 v64, v0
	v_mov_b32_e32 v65, v0
	v_mov_b32_e32 v66, v0
	v_mov_b32_e32 v67, v0
	v_mov_b32_e32 v68, v0
	v_mov_b32_e32 v69, v0
	v_mov_b32_e32 v70, v0
	v_mov_b32_e32 v71, v0
	v_mov_b32_e32 v72, v0
	v_mov_b32_e32 v73, v0
	v_mov_b32_e32 v82, v0
	v_mov_b32_e32 v83, v0
	v_mov_b32_e32 v84, v0
	v_mov_b32_e32 v85, v0
	v_mov_b32_e32 v86, v0
	v_mov_b32_e32 v87, v0
	v_mov_b32_e32 v88, v0
	v_mov_b32_e32 v89, v0
	v_mov_b32_e32 v98, v0
	v_mov_b32_e32 v99, v0
	v_mov_b32_e32 v100, v0
	v_mov_b32_e32 v101, v0
	v_mov_b32_e32 v102, v0
	v_mov_b32_e32 v103, v0
	v_mov_b32_e32 v104, v0
	v_mov_b32_e32 v105, v0
	v_mov_b32_e32 v114, v0
	v_mov_b32_e32 v115, v0
	v_mov_b32_e32 v116, v0
	v_mov_b32_e32 v117, v0
	v_mov_b32_e32 v118, v0
	v_mov_b32_e32 v119, v0
	v_mov_b32_e32 v120, v0
	v_mov_b32_e32 v121, v0
	v_mov_b32_e32 v74, v0
	v_mov_b32_e32 v75, v0
	v_mov_b32_e32 v76, v0
	v_mov_b32_e32 v77, v0
	v_mov_b32_e32 v78, v0
	v_mov_b32_e32 v79, v0
	v_mov_b32_e32 v80, v0
	v_mov_b32_e32 v81, v0
	v_mov_b32_e32 v90, v0
	v_mov_b32_e32 v91, v0
	v_mov_b32_e32 v92, v0
	v_mov_b32_e32 v93, v0
	v_mov_b32_e32 v94, v0
	v_mov_b32_e32 v95, v0
	v_mov_b32_e32 v96, v0
	v_mov_b32_e32 v97, v0
	v_mov_b32_e32 v106, v0
	v_mov_b32_e32 v107, v0
	v_mov_b32_e32 v108, v0
	v_mov_b32_e32 v109, v0
	v_mov_b32_e32 v110, v0
	v_mov_b32_e32 v111, v0
	v_mov_b32_e32 v112, v0
	v_mov_b32_e32 v113, v0
	v_mov_b32_e32 v122, v0
	v_mov_b32_e32 v123, v0
	v_mov_b32_e32 v124, v0
	v_mov_b32_e32 v125, v0
	v_mov_b32_e32 v126, v0
	v_mov_b32_e32 v127, v0
	v_mov_b32_e32 v128, v0
	v_mov_b32_e32 v129, v0
.LBB0_411:
	s_add_i32 vcc_lo, s46, 2
	s_add_u32 s38, s44, 0x8000
	s_addc_u32 s39, s45, 0
	s_add_i32 vcc_hi, 0, 0x10000
	s_cmp_eq_u32 s92, s46
	s_cselect_b32 s47, s79, s39
	s_cselect_b32 s46, s78, s38
	v_add_u32_e32 v149, vcc_hi, v146
	s_cselect_b32 s39, s81, s49
	s_cselect_b32 s38, s80, s48
	s_add_i32 s61, 0, 0x14000
	ds_read_b128 v[142:145], v149
	ds_read_b128 v[150:153], v149 offset:1024
	ds_read_b128 v[154:157], v149 offset:2048
	ds_read_b128 v[158:161], v149 offset:3072
	v_add_u32_e32 v149, s61, v146
	ds_read_b128 v[170:173], v149
	ds_read_b128 v[174:177], v149 offset:1024
	ds_read_b128 v[178:181], v149 offset:2048
	ds_read_b128 v[182:185], v149 offset:3072
	v_lshl_add_u64 v[228:229], s[44:45], 0, v[140:141]
	s_add_i32 m0, s82, 0xc000
	ds_read_b128 v[196:199], v148
	ds_read_b128 v[200:203], v148 offset:1024
	ds_read_b128 v[204:207], v148 offset:2048
	ds_read_b128 v[208:211], v148 offset:3072
	ds_read_b128 v[212:215], v148 offset:4096
	ds_read_b128 v[216:219], v148 offset:5120
	ds_read_b128 v[220:223], v148 offset:6144
	ds_read_b128 v[224:227], v148 offset:7168
	global_load_lds_dwordx4 v[228:229], off
	v_lshl_add_u64 v[228:229], s[44:45], 0, v[138:139]
	s_add_i32 m0, s82, 0xe000
	s_nop 0
	global_load_lds_dwordx4 v[228:229], off
	s_waitcnt vmcnt(8)
	s_waitcnt lgkmcnt(0)
	s_barrier
	v_mfma_f32_16x16x32_bf16 v[126:129], v[142:145], v[196:199], v[126:129]
	v_mfma_f32_16x16x32_bf16 v[122:125], v[154:157], v[196:199], v[122:125]
	v_mfma_f32_16x16x32_bf16 v[110:113], v[142:145], v[204:207], v[110:113]
	v_mfma_f32_16x16x32_bf16 v[106:109], v[154:157], v[204:207], v[106:109]
	v_mfma_f32_16x16x32_bf16 v[94:97], v[142:145], v[212:215], v[94:97]
	v_mfma_f32_16x16x32_bf16 v[90:93], v[154:157], v[212:215], v[90:93]
	v_mfma_f32_16x16x32_bf16 v[78:81], v[142:145], v[220:223], v[78:81]
	v_mfma_f32_16x16x32_bf16 v[74:77], v[154:157], v[220:223], v[74:77]
	v_mfma_f32_16x16x32_bf16 v[126:129], v[150:153], v[200:203], v[126:129]
	v_mfma_f32_16x16x32_bf16 v[122:125], v[158:161], v[200:203], v[122:125]
	v_mfma_f32_16x16x32_bf16 v[110:113], v[150:153], v[208:211], v[110:113]
	v_mfma_f32_16x16x32_bf16 v[106:109], v[158:161], v[208:211], v[106:109]
	v_mfma_f32_16x16x32_bf16 v[94:97], v[150:153], v[216:219], v[94:97]
	v_mfma_f32_16x16x32_bf16 v[90:93], v[158:161], v[216:219], v[90:93]
	v_mfma_f32_16x16x32_bf16 v[78:81], v[150:153], v[224:227], v[78:81]
	v_mfma_f32_16x16x32_bf16 v[74:77], v[158:161], v[224:227], v[74:77]
	v_mfma_f32_16x16x32_bf16 v[118:121], v[170:173], v[196:199], v[118:121]
	v_mfma_f32_16x16x32_bf16 v[114:117], v[178:181], v[196:199], v[114:117]
	v_mfma_f32_16x16x32_bf16 v[102:105], v[170:173], v[204:207], v[102:105]
	v_mfma_f32_16x16x32_bf16 v[98:101], v[178:181], v[204:207], v[98:101]
	v_mfma_f32_16x16x32_bf16 v[86:89], v[170:173], v[212:215], v[86:89]
	v_mfma_f32_16x16x32_bf16 v[82:85], v[178:181], v[212:215], v[82:85]
	v_mfma_f32_16x16x32_bf16 v[70:73], v[170:173], v[220:223], v[70:73]
	v_mfma_f32_16x16x32_bf16 v[66:69], v[178:181], v[220:223], v[66:69]
	v_mfma_f32_16x16x32_bf16 v[118:121], v[174:177], v[200:203], v[118:121]
	v_mfma_f32_16x16x32_bf16 v[114:117], v[182:185], v[200:203], v[114:117]
	v_mfma_f32_16x16x32_bf16 v[102:105], v[174:177], v[208:211], v[102:105]
	v_mfma_f32_16x16x32_bf16 v[98:101], v[182:185], v[208:211], v[98:101]
	v_mfma_f32_16x16x32_bf16 v[86:89], v[174:177], v[216:219], v[86:89]
	v_mfma_f32_16x16x32_bf16 v[82:85], v[182:185], v[216:219], v[82:85]
	v_mfma_f32_16x16x32_bf16 v[70:73], v[174:177], v[224:227], v[70:73]
	v_mfma_f32_16x16x32_bf16 v[66:69], v[182:185], v[224:227], v[66:69]
	s_barrier
; #define PG8_STAGE(bufoff, gbase, voff) do { _Pragma("unroll") for (int _i = 0; _i < 2; ++_i) \
;         __builtin_amdgcn_global_load_lds((const unsigned*)((const char*)(gbase) + (voff)[_i]), (PG8_LAS unsigned*)(lds + (bufoff) + ldsw + _i * 8192), 16, 0, 0); } while (0)
; #define PG8_LDA(dst, b, h) do { _Pragma("unroll") for (int m = 0; m < 4; ++m) _Pragma("unroll") for (int k = 0; k < 2; ++k) dst[m][k] = *(const PG8_LAS bf16x8*)(lds + PG8_SA(b, h) + aoff + m * 2048 + k * 1024); } while (0)
; #define PG8_LDB(dst, b, h) do { _Pragma("unroll") for (int n = 0; n < 2; ++n) _Pragma("unroll") for (int k = 0; k < 2; ++k) dst[n][k] = *(const PG8_LAS bf16x8*)(lds + PG8_SB(b, h) + boff + n * 2048 + k * 1024); } while (0)
; #define PG8_MMA(ai, bj, At, Bt) do { __builtin_amdgcn_s_setprio(1); _Pragma("unroll") for (int m = 0; m < 4; ++m) _Pragma("unroll") for (int n = 0; n < 2; ++n) _Pragma("unroll") for (int k = 0; k < 2; ++k) \
;         acc[ai][bj][m][n] = __builtin_amdgcn_mfma_f32_16x16x32_bf16(Bt[n][k], At[m][k], acc[ai][bj][m][n], 0, 0, 0); __builtin_amdgcn_s_setprio(0); } while (0)
; #define PG8_WAIT_V(n) asm volatile("s_waitcnt vmcnt(" #n ")" ::: "memory")
; #define PG8_WAIT_L(n) asm volatile("s_waitcnt lgkmcnt(" #n ")" ::: "memory")
; #define PG8_BAR __builtin_amdgcn_s_barrier()
; #define PG8_SCHED __builtin_amdgcn_sched_barrier(0)
; template <class Epi, class Sched, bool ALIGN_EPI = false, bool SP2 = false>
; __device__ __forceinline__ void gemm_phase(PG8_LAS unsigned char* lds, const Gemm g, const Sched& S, const Epi& E) {
;     ...
;             PG8_WAIT_V(8); PG8_WAIT_L(0); PG8_BAR; PG8_MMA(0, 0, At, B0); PG8_MMA(0, 1, At, B1); PG8_BAR; PG8_SCHED;
;             PG8_LDA(At, 0, 1); PG8_STAGE(PG8_SB(0, 0), b2, voffB); PG8_STAGE(PG8_SB(0, 1), b2 + hstep, voffB); PG8_STAGE(PG8_SA(0, 0), a2, voffA);
;             PG8_WAIT_V(8); PG8_WAIT_L(0); PG8_BAR; PG8_MMA(1, 0, At, B0); PG8_MMA(1, 1, At, B1); PG8_BAR; PG8_SCHED;
;             PG8_LDB(B0, 1, 0); PG8_LDB(B1, 1, 1); PG8_SCHED; PG8_LDA(At, 1, 0); PG8_STAGE(PG8_SA(0, 1), a2 + hstep, voffA);
;             PG8_WAIT_V(8); PG8_WAIT_L(0); PG8_BAR; PG8_MMA(0, 0, At, B0); PG8_MMA(0, 1, At, B1); PG8_BAR; PG8_SCHED;
	s_add_i32 vcc_hi, vcc_hi, s51
	v_lshl_add_u64 v[228:229], s[38:39], 0, v[132:133]
	s_mov_b32 m0, vcc_hi
	ds_read_b128 v[196:199], v148 offset:16384
	ds_read_b128 v[200:203], v148 offset:17408
	ds_read_b128 v[204:207], v148 offset:18432
	ds_read_b128 v[208:211], v148 offset:19456
	ds_read_b128 v[212:215], v148 offset:20480
	ds_read_b128 v[216:219], v148 offset:21504
	ds_read_b128 v[220:223], v148 offset:22528
	ds_read_b128 v[224:227], v148 offset:23552
	global_load_lds_dwordx4 v[228:229], off
	s_add_i32 m0, vcc_hi, 0x2000
	v_lshl_add_u64 v[230:231], s[38:39], 0, v[136:137]
	s_add_u32 s38, s38, s8
	s_addc_u32 s39, s39, 0
	s_add_i32 s61, s61, s51
	global_load_lds_dwordx4 v[230:231], off
	v_lshl_add_u64 v[232:233], s[38:39], 0, v[132:133]
	s_mov_b32 m0, s61
	v_lshl_add_u64 v[234:235], s[38:39], 0, v[136:137]
	global_load_lds_dwordx4 v[232:233], off
	s_add_i32 m0, s61, 0x2000
	v_lshl_add_u64 v[236:237], s[46:47], 0, v[130:131]
	global_load_lds_dwordx4 v[234:235], off
	s_mov_b32 m0, s82
	v_lshl_add_u64 v[238:239], s[46:47], 0, v[134:135]
	global_load_lds_dwordx4 v[236:237], off
	s_mov_b32 m0, s83
	s_nop 0
	global_load_lds_dwordx4 v[238:239], off
	s_waitcnt vmcnt(8)
	s_waitcnt lgkmcnt(0)
	s_barrier
	v_mfma_f32_16x16x32_bf16 v[62:65], v[142:145], v[196:199], v[62:65]
	v_mfma_f32_16x16x32_bf16 v[58:61], v[154:157], v[196:199], v[58:61]
	v_mfma_f32_16x16x32_bf16 v[46:49], v[142:145], v[204:207], v[46:49]
	v_mfma_f32_16x16x32_bf16 v[42:45], v[154:157], v[204:207], v[42:45]
	v_mfma_f32_16x16x32_bf16 v[28:31], v[142:145], v[212:215], v[28:31]
	v_mfma_f32_16x16x32_bf16 v[24:27], v[154:157], v[212:215], v[24:27]
	v_mfma_f32_16x16x32_bf16 v[12:15], v[142:145], v[220:223], v[12:15]
	v_mfma_f32_16x16x32_bf16 v[8:11], v[154:157], v[220:223], v[8:11]
	v_mfma_f32_16x16x32_bf16 v[62:65], v[150:153], v[200:203], v[62:65]
	v_mfma_f32_16x16x32_bf16 v[58:61], v[158:161], v[200:203], v[58:61]
	v_mfma_f32_16x16x32_bf16 v[46:49], v[150:153], v[208:211], v[46:49]
	v_mfma_f32_16x16x32_bf16 v[42:45], v[158:161], v[208:211], v[42:45]
	v_mfma_f32_16x16x32_bf16 v[28:31], v[150:153], v[216:219], v[28:31]
	v_mfma_f32_16x16x32_bf16 v[24:27], v[158:161], v[216:219], v[24:27]
	v_mfma_f32_16x16x32_bf16 v[12:15], v[150:153], v[224:227], v[12:15]
	v_mfma_f32_16x16x32_bf16 v[8:11], v[158:161], v[224:227], v[8:11]
	v_mfma_f32_16x16x32_bf16 v[54:57], v[170:173], v[196:199], v[54:57]
	v_mfma_f32_16x16x32_bf16 v[50:53], v[178:181], v[196:199], v[50:53]
	v_mfma_f32_16x16x32_bf16 v[38:41], v[170:173], v[204:207], v[38:41]
	v_mfma_f32_16x16x32_bf16 v[34:37], v[178:181], v[204:207], v[34:37]
	v_mfma_f32_16x16x32_bf16 v[20:23], v[170:173], v[212:215], v[20:23]
	v_mfma_f32_16x16x32_bf16 v[16:19], v[178:181], v[212:215], v[16:19]
	v_mfma_f32_16x16x32_bf16 v[4:7], v[170:173], v[220:223], v[4:7]
	v_mfma_f32_16x16x32_bf16 v[0:3], v[178:181], v[220:223], v[0:3]
	v_mfma_f32_16x16x32_bf16 v[54:57], v[174:177], v[200:203], v[54:57]
	v_mfma_f32_16x16x32_bf16 v[50:53], v[182:185], v[200:203], v[50:53]
	v_mfma_f32_16x16x32_bf16 v[38:41], v[174:177], v[208:211], v[38:41]
	v_mfma_f32_16x16x32_bf16 v[34:37], v[182:185], v[208:211], v[34:37]
	v_mfma_f32_16x16x32_bf16 v[20:23], v[174:177], v[216:219], v[20:23]
	v_mfma_f32_16x16x32_bf16 v[16:19], v[182:185], v[216:219], v[16:19]
	v_mfma_f32_16x16x32_bf16 v[4:7], v[174:177], v[224:227], v[4:7]
	v_mfma_f32_16x16x32_bf16 v[0:3], v[182:185], v[224:227], v[0:3]
	s_barrier
	s_add_i32 s61, 0, 0x18000
	v_add_u32_e32 v149, s61, v146
	s_add_i32 vcc_hi, 0, 0x1c000
	ds_read_b128 v[142:145], v149
	ds_read_b128 v[150:153], v149 offset:1024
	ds_read_b128 v[154:157], v149 offset:2048
	ds_read_b128 v[158:161], v149 offset:3072
	v_add_u32_e32 v149, vcc_hi, v146
	ds_read_b128 v[170:173], v149
	ds_read_b128 v[174:177], v149 offset:1024
	ds_read_b128 v[178:181], v149 offset:2048
	ds_read_b128 v[182:185], v149 offset:3072
	s_add_u32 s38, s46, 0x4000
	s_addc_u32 s39, s47, 0
	s_mov_b32 m0, s87
	v_lshl_add_u64 v[240:241], s[38:39], 0, v[130:131]
	ds_read_b128 v[196:199], v148 offset:32768
	ds_read_b128 v[200:203], v148 offset:33792
	ds_read_b128 v[204:207], v148 offset:34816
	ds_read_b128 v[208:211], v148 offset:35840
	ds_read_b128 v[212:215], v148 offset:36864
	ds_read_b128 v[216:219], v148 offset:37888
	ds_read_b128 v[220:223], v148 offset:38912
	ds_read_b128 v[224:227], v148 offset:39936
	global_load_lds_dwordx4 v[240:241], off
	v_lshl_add_u64 v[240:241], s[38:39], 0, v[134:135]
	s_mov_b32 m0, s88
	s_nop 0
	global_load_lds_dwordx4 v[240:241], off
	s_waitcnt vmcnt(8)
	s_waitcnt lgkmcnt(0)
	s_barrier
; #define PG8_STAGE(bufoff, gbase, voff) do { _Pragma("unroll") for (int _i = 0; _i < 2; ++_i) \
;         __builtin_amdgcn_global_load_lds((const unsigned*)((const char*)(gbase) + (voff)[_i]), (PG8_LAS unsigned*)(lds + (bufoff) + ldsw + _i * 8192), 16, 0, 0); } while (0)
; #define PG8_LDA(dst, b, h) do { _Pragma("unroll") for (int m = 0; m < 4; ++m) _Pragma("unroll") for (int k = 0; k < 2; ++k) dst[m][k] = *(const PG8_LAS bf16x8*)(lds + PG8_SA(b, h) + aoff + m * 2048 + k * 1024); } while (0)
; #define PG8_LDB(dst, b, h) do { _Pragma("unroll") for (int n = 0; n < 2; ++n) _Pragma("unroll") for (int k = 0; k < 2; ++k) dst[n][k] = *(const PG8_LAS bf16x8*)(lds + PG8_SB(b, h) + boff + n * 2048 + k * 1024); } while (0)
; #define PG8_MMA(ai, bj, At, Bt) do { __builtin_amdgcn_s_setprio(1); _Pragma("unroll") for (int m = 0; m < 4; ++m) _Pragma("unroll") for (int n = 0; n < 2; ++n) _Pragma("unroll") for (int k = 0; k < 2; ++k) \
;         acc[ai][bj][m][n] = __builtin_amdgcn_mfma_f32_16x16x32_bf16(Bt[n][k], At[m][k], acc[ai][bj][m][n], 0, 0, 0); __builtin_amdgcn_s_setprio(0); } while (0)
; #define PG8_WAIT_V(n) asm volatile("s_waitcnt vmcnt(" #n ")" ::: "memory")
; #define PG8_WAIT_L(n) asm volatile("s_waitcnt lgkmcnt(" #n ")" ::: "memory")
; #define PG8_BAR __builtin_amdgcn_s_barrier()
; #define PG8_SCHED __builtin_amdgcn_sched_barrier(0)
; template <class Epi, class Sched, bool ALIGN_EPI = false, bool SP2 = false>
; __device__ __forceinline__ void gemm_phase(PG8_LAS unsigned char* lds, const Gemm g, const Sched& S, const Epi& E) {
;     ...
;             PG8_LDB(B0, 1, 0); PG8_LDB(B1, 1, 1); PG8_SCHED; PG8_LDA(At, 1, 0); PG8_STAGE(PG8_SA(0, 1), a2 + hstep, voffA);
;             PG8_WAIT_V(8); PG8_WAIT_L(0); PG8_BAR; PG8_MMA(0, 0, At, B0); PG8_MMA(0, 1, At, B1); PG8_BAR; PG8_SCHED;
;             PG8_LDA(At, 1, 1); PG8_STAGE(PG8_SB(1, 0), b3, voffB); PG8_STAGE(PG8_SB(1, 1), b3 + hstep, voffB); PG8_STAGE(PG8_SA(1, 0), a3, voffA);
;             PG8_WAIT_V(8); PG8_WAIT_L(0); PG8_BAR; PG8_MMA(1, 0, At, B0); PG8_MMA(1, 1, At, B1); PG8_BAR; PG8_SCHED;
	v_mfma_f32_16x16x32_bf16 v[126:129], v[142:145], v[196:199], v[126:129]
	v_mfma_f32_16x16x32_bf16 v[122:125], v[154:157], v[196:199], v[122:125]
	v_mfma_f32_16x16x32_bf16 v[110:113], v[142:145], v[204:207], v[110:113]
	v_mfma_f32_16x16x32_bf16 v[106:109], v[154:157], v[204:207], v[106:109]
	v_mfma_f32_16x16x32_bf16 v[94:97], v[142:145], v[212:215], v[94:97]
	v_mfma_f32_16x16x32_bf16 v[90:93], v[154:157], v[212:215], v[90:93]
	v_mfma_f32_16x16x32_bf16 v[78:81], v[142:145], v[220:223], v[78:81]
	v_mfma_f32_16x16x32_bf16 v[74:77], v[154:157], v[220:223], v[74:77]
	v_mfma_f32_16x16x32_bf16 v[126:129], v[150:153], v[200:203], v[126:129]
	v_mfma_f32_16x16x32_bf16 v[122:125], v[158:161], v[200:203], v[122:125]
	v_mfma_f32_16x16x32_bf16 v[110:113], v[150:153], v[208:211], v[110:113]
	v_mfma_f32_16x16x32_bf16 v[106:109], v[158:161], v[208:211], v[106:109]
	v_mfma_f32_16x16x32_bf16 v[94:97], v[150:153], v[216:219], v[94:97]
	v_mfma_f32_16x16x32_bf16 v[90:93], v[158:161], v[216:219], v[90:93]
	v_mfma_f32_16x16x32_bf16 v[78:81], v[150:153], v[224:227], v[78:81]
	v_mfma_f32_16x16x32_bf16 v[74:77], v[158:161], v[224:227], v[74:77]
	v_mfma_f32_16x16x32_bf16 v[118:121], v[170:173], v[196:199], v[118:121]
	v_mfma_f32_16x16x32_bf16 v[114:117], v[178:181], v[196:199], v[114:117]
	v_mfma_f32_16x16x32_bf16 v[102:105], v[170:173], v[204:207], v[102:105]
	v_mfma_f32_16x16x32_bf16 v[98:101], v[178:181], v[204:207], v[98:101]
	v_mfma_f32_16x16x32_bf16 v[86:89], v[170:173], v[212:215], v[86:89]
	v_mfma_f32_16x16x32_bf16 v[82:85], v[178:181], v[212:215], v[82:85]
	v_mfma_f32_16x16x32_bf16 v[70:73], v[170:173], v[220:223], v[70:73]
	v_mfma_f32_16x16x32_bf16 v[66:69], v[178:181], v[220:223], v[66:69]
	v_mfma_f32_16x16x32_bf16 v[118:121], v[174:177], v[200:203], v[118:121]
	v_mfma_f32_16x16x32_bf16 v[114:117], v[182:185], v[200:203], v[114:117]
	v_mfma_f32_16x16x32_bf16 v[102:105], v[174:177], v[208:211], v[102:105]
	v_mfma_f32_16x16x32_bf16 v[98:101], v[182:185], v[208:211], v[98:101]
	v_mfma_f32_16x16x32_bf16 v[86:89], v[174:177], v[216:219], v[86:89]
	v_mfma_f32_16x16x32_bf16 v[82:85], v[182:185], v[216:219], v[82:85]
	v_mfma_f32_16x16x32_bf16 v[70:73], v[174:177], v[224:227], v[70:73]
	v_mfma_f32_16x16x32_bf16 v[66:69], v[182:185], v[224:227], v[66:69]
	s_barrier
	s_add_i32 s38, s61, s51
	v_lshl_add_u64 v[228:229], v[228:229], 0, s[34:35]
	s_mov_b32 m0, s38
	ds_read_b128 v[196:199], v148 offset:49152
	ds_read_b128 v[200:203], v148 offset:50176
	ds_read_b128 v[204:207], v148 offset:51200
	ds_read_b128 v[208:211], v148 offset:52224
	ds_read_b128 v[212:215], v148 offset:53248
	ds_read_b128 v[216:219], v148 offset:54272
	ds_read_b128 v[220:223], v148 offset:55296
	ds_read_b128 v[224:227], v148 offset:56320
	global_load_lds_dwordx4 v[228:229], off
	v_lshl_add_u64 v[228:229], v[230:231], 0, s[34:35]
	s_add_i32 m0, s38, 0x2000
	s_add_i32 s38, vcc_hi, s51
	global_load_lds_dwordx4 v[228:229], off
	v_lshl_add_u64 v[228:229], v[232:233], 0, s[34:35]
	s_mov_b32 m0, s38
	s_nop 0
	global_load_lds_dwordx4 v[228:229], off
	v_lshl_add_u64 v[228:229], v[234:235], 0, s[34:35]
	s_add_i32 m0, s38, 0x2000
	s_nop 0
	global_load_lds_dwordx4 v[228:229], off
	v_lshl_add_u64 v[228:229], v[236:237], 0, s[100:101]
	s_mov_b32 m0, s90
	s_nop 0
	global_load_lds_dwordx4 v[228:229], off
	v_lshl_add_u64 v[228:229], v[238:239], 0, s[100:101]
	s_mov_b32 m0, s91
	s_nop 0
	global_load_lds_dwordx4 v[228:229], off
	s_waitcnt vmcnt(8)
	s_waitcnt lgkmcnt(0)
	s_barrier
	v_mfma_f32_16x16x32_bf16 v[62:65], v[142:145], v[196:199], v[62:65]
	v_mfma_f32_16x16x32_bf16 v[58:61], v[154:157], v[196:199], v[58:61]
	v_mfma_f32_16x16x32_bf16 v[46:49], v[142:145], v[204:207], v[46:49]
	v_mfma_f32_16x16x32_bf16 v[42:45], v[154:157], v[204:207], v[42:45]
	v_mfma_f32_16x16x32_bf16 v[28:31], v[142:145], v[212:215], v[28:31]
	v_mfma_f32_16x16x32_bf16 v[24:27], v[154:157], v[212:215], v[24:27]
	v_mfma_f32_16x16x32_bf16 v[12:15], v[142:145], v[220:223], v[12:15]
	v_mfma_f32_16x16x32_bf16 v[8:11], v[154:157], v[220:223], v[8:11]
	v_mfma_f32_16x16x32_bf16 v[62:65], v[150:153], v[200:203], v[62:65]
	v_mfma_f32_16x16x32_bf16 v[58:61], v[158:161], v[200:203], v[58:61]
	v_mfma_f32_16x16x32_bf16 v[46:49], v[150:153], v[208:211], v[46:49]
	v_mfma_f32_16x16x32_bf16 v[42:45], v[158:161], v[208:211], v[42:45]
	v_mfma_f32_16x16x32_bf16 v[28:31], v[150:153], v[216:219], v[28:31]
	v_mfma_f32_16x16x32_bf16 v[24:27], v[158:161], v[216:219], v[24:27]
	v_mfma_f32_16x16x32_bf16 v[12:15], v[150:153], v[224:227], v[12:15]
	v_mfma_f32_16x16x32_bf16 v[8:11], v[158:161], v[224:227], v[8:11]
	v_mfma_f32_16x16x32_bf16 v[54:57], v[170:173], v[196:199], v[54:57]
	v_mfma_f32_16x16x32_bf16 v[50:53], v[178:181], v[196:199], v[50:53]
	v_mfma_f32_16x16x32_bf16 v[38:41], v[170:173], v[204:207], v[38:41]
	v_mfma_f32_16x16x32_bf16 v[34:37], v[178:181], v[204:207], v[34:37]
	v_mfma_f32_16x16x32_bf16 v[20:23], v[170:173], v[212:215], v[20:23]
	v_mfma_f32_16x16x32_bf16 v[16:19], v[178:181], v[212:215], v[16:19]
	v_mfma_f32_16x16x32_bf16 v[4:7], v[170:173], v[220:223], v[4:7]
	v_mfma_f32_16x16x32_bf16 v[0:3], v[178:181], v[220:223], v[0:3]
	v_mfma_f32_16x16x32_bf16 v[54:57], v[174:177], v[200:203], v[54:57]
	v_mfma_f32_16x16x32_bf16 v[50:53], v[182:185], v[200:203], v[50:53]
	v_mfma_f32_16x16x32_bf16 v[38:41], v[174:177], v[208:211], v[38:41]
	v_mfma_f32_16x16x32_bf16 v[34:37], v[182:185], v[208:211], v[34:37]
	v_mfma_f32_16x16x32_bf16 v[20:23], v[174:177], v[216:219], v[20:23]
	v_mfma_f32_16x16x32_bf16 v[16:19], v[182:185], v[216:219], v[16:19]
	v_mfma_f32_16x16x32_bf16 v[4:7], v[174:177], v[224:227], v[4:7]
	v_mfma_f32_16x16x32_bf16 v[0:3], v[182:185], v[224:227], v[0:3]
	s_barrier
	s_add_u32 s48, s48, 0x100
	s_addc_u32 s49, s49, 0
	s_add_u32 s44, s44, 0x10000
	s_addc_u32 s45, s45, 0
	s_cmp_ge_u32 vcc_lo, s85
	s_mov_b32 s46, vcc_lo
	s_cbranch_scc0 .LBB0_411
	s_and_b64 vcc, exec, s[42:43]
	s_cbranch_vccz .LBB0_414
	s_barrier

; __device__ __forceinline__ unsigned cvt_pk_bf16(float lo, float hi) { unsigned r; asm volatile("v_cvt_pk_bf16_f32 %0, %1, %2" : "=v"(r) : "v"(lo), "v"(hi)); return r; }
; #define GAS __attribute__((address_space(1)))
; __device__ __forceinline__ float silu_mul(float g, float u) { const float e = __builtin_amdgcn_exp2f(-1.4426950408889634f * g); return g * __builtin_amdgcn_rcpf(1.0f + e) * u; }
;     __device__ __forceinline__ void operator()(const f32x4 (&acc)[2][2][4][2], const Unit& u, int wr, int wc, int fr, int fq, const float (&pre)[8]) const {
;         const int row0 = u.pm * 256 + wr * 64 + fr, col0 = u.pn * 128 + wc * 32 + 8 * fq;
; #pragma unroll
;         for (int ai = 0; ai < 2; ++ai)
; #pragma unroll
;             for (int m = 0; m < 4; ++m) {
;                 const float rsc = pre[ai * 4 + m];
;                 const f32x4 g0 = acc[ai][0][m][0] * rsc, g1 = acc[ai][0][m][1] * rsc, u0 = acc[ai][1][m][0] * rsc, u1 = acc[ai][1][m][1] * rsc;
;                 u32x4 w; w.x = cvt_pk_bf16(silu_mul(g0[0], u0[0]), silu_mul(g0[1], u0[1])); w.y = cvt_pk_bf16(silu_mul(g0[2], u0[2]), silu_mul(g0[3], u0[3]));
;                 w.z = cvt_pk_bf16(silu_mul(g1[0], u1[0]), silu_mul(g1[1], u1[1])); w.w = cvt_pk_bf16(silu_mul(g1[2], u1[2]), silu_mul(g1[3], u1[3]));
;                 *(GAS u32x4*)(O + (size_t)(row0 + ai * 128 + m * 16) * DFF + col0) = w; }
.LBB0_447:
	v_pk_mul_f32 v[126:127], v[158:159], v[126:127] op_sel_hi:[0,1]
	v_mul_f32_e32 v153, 0xbfb8aa3b, v126
	v_exp_f32_e32 v153, v153
	v_pk_mul_f32 v[118:119], v[158:159], v[118:119] op_sel_hi:[0,1]
	v_pk_mul_f32 v[128:129], v[158:159], v[128:129] op_sel_hi:[0,1]
	v_pk_mul_f32 v[120:121], v[158:159], v[120:121] op_sel_hi:[0,1]
	v_add_f32_e32 v153, 1.0, v153
	v_rcp_f32_e32 v153, v153
	v_pk_mul_f32 v[122:123], v[158:159], v[122:123] op_sel_hi:[0,1]
	v_pk_mul_f32 v[114:115], v[158:159], v[114:115] op_sel_hi:[0,1]
	v_pk_mul_f32 v[124:125], v[158:159], v[124:125] op_sel_hi:[0,1]
	v_mul_f32_e32 v126, v126, v153
	v_mul_f32_e32 v118, v126, v118
	v_mul_f32_e32 v126, 0xbfb8aa3b, v127
	v_exp_f32_e32 v126, v126
	v_pk_mul_f32 v[116:117], v[158:159], v[116:117] op_sel_hi:[0,1]
	v_lshl_or_b32 v160, s44, 7, v147
	v_lshl_add_u32 v151, s46, 8, v33
	v_add_f32_e32 v126, 1.0, v126
	v_rcp_f32_e32 v126, v126
	v_ashrrev_i32_e32 v161, 31, v160
	v_pk_mul_f32 v[110:111], v[156:157], v[110:111] op_sel_hi:[0,1]
	v_pk_mul_f32 v[102:103], v[156:157], v[102:103] op_sel_hi:[0,1]
	v_mul_f32_e32 v126, v127, v126
	v_mul_f32_e32 v119, v126, v119
	v_cvt_pk_bf16_f32 v118, v118, v119
	v_mul_f32_e32 v119, 0xbfb8aa3b, v128
	v_exp_f32_e32 v119, v119
	v_pk_mul_f32 v[112:113], v[156:157], v[112:113] op_sel_hi:[0,1]
	v_pk_mul_f32 v[104:105], v[156:157], v[104:105] op_sel_hi:[0,1]
	v_pk_mul_f32 v[106:107], v[156:157], v[106:107] op_sel_hi:[0,1]
	v_add_f32_e32 v119, 1.0, v119
	v_rcp_f32_e32 v119, v119
	v_pk_mul_f32 v[108:109], v[156:157], v[108:109] op_sel_hi:[0,1]
	v_pk_mul_f32 v[94:95], v[154:155], v[94:95] op_sel_hi:[0,1]
	v_pk_mul_f32 v[86:87], v[154:155], v[86:87] op_sel_hi:[0,1]
	v_mul_f32_e32 v119, v128, v119
	v_mul_f32_e32 v119, v119, v120
	v_mul_f32_e32 v120, 0xbfb8aa3b, v129
	v_exp_f32_e32 v120, v120
	v_pk_mul_f32 v[96:97], v[154:155], v[96:97] op_sel_hi:[0,1]
	v_pk_mul_f32 v[88:89], v[154:155], v[88:89] op_sel_hi:[0,1]
	v_pk_mul_f32 v[90:91], v[154:155], v[90:91] op_sel_hi:[0,1]
	v_add_f32_e32 v120, 1.0, v120
	v_rcp_f32_e32 v120, v120
	v_pk_mul_f32 v[92:93], v[154:155], v[92:93] op_sel_hi:[0,1]
	v_pk_mul_f32 v[78:79], v[152:153], v[78:79] op_sel_hi:[0,1]
	v_pk_mul_f32 v[70:71], v[152:153], v[70:71] op_sel_hi:[0,1]
	v_mul_f32_e32 v120, v129, v120
	v_mul_f32_e32 v120, v120, v121
	v_cvt_pk_bf16_f32 v119, v119, v120
	v_mul_f32_e32 v120, 0xbfb8aa3b, v122
	v_exp_f32_e32 v120, v120
	v_pk_mul_f32 v[80:81], v[152:153], v[80:81] op_sel_hi:[0,1]
	v_pk_mul_f32 v[72:73], v[152:153], v[72:73] op_sel_hi:[0,1]
	v_pk_mul_f32 v[74:75], v[152:153], v[74:75] op_sel_hi:[0,1]
	v_add_f32_e32 v120, 1.0, v120
	v_rcp_f32_e32 v120, v120
	v_pk_mul_f32 v[76:77], v[152:153], v[76:77] op_sel_hi:[0,1]
	v_pk_mul_f32 v[62:63], v[150:151], v[62:63] op_sel_hi:[0,1]
	v_pk_mul_f32 v[54:55], v[150:151], v[54:55] op_sel_hi:[0,1]
	v_mul_f32_e32 v120, v122, v120
	v_mul_f32_e32 v114, v120, v114
	v_mul_f32_e32 v120, 0xbfb8aa3b, v123
	v_exp_f32_e32 v120, v120
	v_pk_mul_f32 v[64:65], v[150:151], v[64:65] op_sel_hi:[0,1]
	v_pk_mul_f32 v[56:57], v[150:151], v[56:57] op_sel_hi:[0,1]
	v_pk_mul_f32 v[58:59], v[150:151], v[58:59] op_sel_hi:[0,1]
	v_add_f32_e32 v120, 1.0, v120
	v_rcp_f32_e32 v120, v120
	v_pk_mul_f32 v[60:61], v[150:151], v[60:61] op_sel_hi:[0,1]
	v_pk_mul_f32 v[46:47], v[148:149], v[46:47] op_sel_hi:[0,1]
	v_pk_mul_f32 v[38:39], v[148:149], v[38:39] op_sel_hi:[0,1]
	v_mul_f32_e32 v120, v123, v120
	v_mul_f32_e32 v115, v120, v115
	v_cvt_pk_bf16_f32 v120, v114, v115
	v_mul_f32_e32 v114, 0xbfb8aa3b, v124
	v_mul_f32_e32 v115, 0xbfb8aa3b, v125
	v_exp_f32_e32 v114, v114
	v_exp_f32_e32 v115, v115
	v_pk_mul_f32 v[48:49], v[148:149], v[48:49] op_sel_hi:[0,1]
	v_pk_mul_f32 v[40:41], v[148:149], v[40:41] op_sel_hi:[0,1]
	v_add_f32_e32 v114, 1.0, v114
	v_add_f32_e32 v115, 1.0, v115
	v_rcp_f32_e32 v114, v114
	v_rcp_f32_e32 v115, v115
	v_pk_mul_f32 v[42:43], v[148:149], v[42:43] op_sel_hi:[0,1]
	v_pk_mul_f32 v[44:45], v[148:149], v[44:45] op_sel_hi:[0,1]
	v_mul_f32_e32 v114, v124, v114
	v_mul_f32_e32 v115, v125, v115
	v_mul_f32_e32 v114, v114, v116
	v_mul_f32_e32 v115, v115, v117
	v_cvt_pk_bf16_f32 v121, v114, v115
	s_mul_i32 s100, s46, 0x158000
	s_mul_hi_u32 s101, s46, 0x158000
	s_add_u32 s100, s64, s100
	s_addc_u32 s101, s65, s101
	v_mov_b64_e32 v[114:115], s[100:101]
	v_mad_i64_i32 v[122:123], s[38:39], v151, s34, v[114:115]
	v_lshrrev_b32_e32 v116, 6, v160
	v_and_b32_e32 v117, 63, v160
	v_lshlrev_b32_e32 v117, 1, v117
	v_lshl_or_b32 v116, v116, 15, v117
	v_mov_b32_e32 v117, 0
	v_lshl_add_u64 v[122:123], v[122:123], 0, v[116:117]
	global_store_dwordx4 v[122:123], v[118:121], off
	v_pk_mul_f32 v[28:29], v[146:147], v[28:29] op_sel_hi:[0,1]
	v_pk_mul_f32 v[20:21], v[146:147], v[20:21] op_sel_hi:[0,1]
	v_pk_mul_f32 v[118:119], v[156:157], v[100:101] op_sel_hi:[0,1]
	v_pk_mul_f32 v[100:101], v[156:157], v[98:99] op_sel_hi:[0,1]
	v_mul_f32_e32 v98, 0xbfb8aa3b, v110
	v_mul_f32_e32 v99, 0xbfb8aa3b, v111
	v_exp_f32_e32 v98, v98
	v_exp_f32_e32 v99, v99
	v_pk_mul_f32 v[30:31], v[146:147], v[30:31] op_sel_hi:[0,1]
	v_pk_mul_f32 v[22:23], v[146:147], v[22:23] op_sel_hi:[0,1]
	v_add_f32_e32 v98, 1.0, v98
	v_add_f32_e32 v99, 1.0, v99
	v_rcp_f32_e32 v98, v98
	v_rcp_f32_e32 v99, v99
	v_pk_mul_f32 v[24:25], v[146:147], v[24:25] op_sel_hi:[0,1]
	v_pk_mul_f32 v[26:27], v[146:147], v[26:27] op_sel_hi:[0,1]
	v_mul_f32_e32 v98, v110, v98
	v_mul_f32_e32 v99, v111, v99
	v_mul_f32_e32 v98, v98, v102
	v_mul_f32_e32 v99, v99, v103
	v_cvt_pk_bf16_f32 v98, v98, v99
	v_mul_f32_e32 v99, 0xbfb8aa3b, v112
	v_mul_f32_e32 v102, 0xbfb8aa3b, v113
	v_exp_f32_e32 v99, v99
	v_exp_f32_e32 v102, v102
	v_pk_mul_f32 v[12:13], v[144:145], v[12:13] op_sel_hi:[0,1]
; __device__ __forceinline__ unsigned cvt_pk_bf16(float lo, float hi) { unsigned r; asm volatile("v_cvt_pk_bf16_f32 %0, %1, %2" : "=v"(r) : "v"(lo), "v"(hi)); return r; }
; #define GAS __attribute__((address_space(1)))
; __device__ __forceinline__ float silu_mul(float g, float u) { const float e = __builtin_amdgcn_exp2f(-1.4426950408889634f * g); return g * __builtin_amdgcn_rcpf(1.0f + e) * u; }
;     __device__ __forceinline__ void operator()(const f32x4 (&acc)[2][2][4][2], const Unit& u, int wr, int wc, int fr, int fq, const float (&pre)[8]) const {
;         const int row0 = u.pm * 256 + wr * 64 + fr, col0 = u.pn * 128 + wc * 32 + 8 * fq;
; #pragma unroll
;         for (int ai = 0; ai < 2; ++ai)
; #pragma unroll
;             for (int m = 0; m < 4; ++m) {
;                 const float rsc = pre[ai * 4 + m];
;                 const f32x4 g0 = acc[ai][0][m][0] * rsc, g1 = acc[ai][0][m][1] * rsc, u0 = acc[ai][1][m][0] * rsc, u1 = acc[ai][1][m][1] * rsc;
;                 u32x4 w; w.x = cvt_pk_bf16(silu_mul(g0[0], u0[0]), silu_mul(g0[1], u0[1])); w.y = cvt_pk_bf16(silu_mul(g0[2], u0[2]), silu_mul(g0[3], u0[3]));
;                 w.z = cvt_pk_bf16(silu_mul(g1[0], u1[0]), silu_mul(g1[1], u1[1])); w.w = cvt_pk_bf16(silu_mul(g1[2], u1[2]), silu_mul(g1[3], u1[3]));
;                 *(GAS u32x4*)(O + (size_t)(row0 + ai * 128 + m * 16) * DFF + col0) = w; }
	v_pk_mul_f32 v[4:5], v[144:145], v[4:5] op_sel_hi:[0,1]
	v_add_f32_e32 v99, 1.0, v99
	v_add_f32_e32 v102, 1.0, v102
	v_rcp_f32_e32 v99, v99
	v_rcp_f32_e32 v102, v102
	v_pk_mul_f32 v[14:15], v[144:145], v[14:15] op_sel_hi:[0,1]
	v_pk_mul_f32 v[6:7], v[144:145], v[6:7] op_sel_hi:[0,1]
	v_mul_f32_e32 v99, v112, v99
	v_mul_f32_e32 v102, v113, v102
	v_mul_f32_e32 v99, v99, v104
	v_mul_f32_e32 v102, v102, v105
	v_cvt_pk_bf16_f32 v99, v99, v102
	v_mul_f32_e32 v102, 0xbfb8aa3b, v106
	v_exp_f32_e32 v102, v102
	v_pk_mul_f32 v[8:9], v[144:145], v[8:9] op_sel_hi:[0,1]
	v_pk_mul_f32 v[10:11], v[144:145], v[10:11] op_sel_hi:[0,1]
	s_mov_b64 s[44:45], -1
	v_add_f32_e32 v102, 1.0, v102
	v_rcp_f32_e32 v102, v102
	s_andn2_b64 vcc, exec, s[80:81]
	v_mul_f32_e32 v102, v106, v102
	v_mul_f32_e32 v100, v102, v100
	v_mul_f32_e32 v102, 0xbfb8aa3b, v107
	v_exp_f32_e32 v102, v102
	s_nop 0
	v_add_f32_e32 v102, 1.0, v102
	v_rcp_f32_e32 v102, v102
	s_nop 0
	v_mul_f32_e32 v102, v107, v102
	v_mul_f32_e32 v101, v102, v101
	v_cvt_pk_bf16_f32 v100, v100, v101
	v_mul_f32_e32 v101, 0xbfb8aa3b, v108
	v_mul_f32_e32 v102, 0xbfb8aa3b, v109
	v_exp_f32_e32 v101, v101
	v_exp_f32_e32 v102, v102
	v_add_f32_e32 v101, 1.0, v101
	v_add_f32_e32 v102, 1.0, v102
	v_rcp_f32_e32 v101, v101
	v_rcp_f32_e32 v102, v102
	v_mul_f32_e32 v101, v108, v101
	v_mul_f32_e32 v102, v109, v102
	v_mul_f32_e32 v101, v101, v118
	v_mul_f32_e32 v102, v102, v119
	v_cvt_pk_bf16_f32 v101, v101, v102
	v_or_b32_e32 v102, 16, v151
	v_mad_i64_i32 v[102:103], s[38:39], v102, s34, v[114:115]
	v_lshl_add_u64 v[102:103], v[102:103], 0, v[116:117]
	global_store_dwordx4 v[102:103], v[98:101], off
	s_nop 1
	v_pk_mul_f32 v[98:99], v[154:155], v[84:85] op_sel_hi:[0,1]
	v_pk_mul_f32 v[84:85], v[154:155], v[82:83] op_sel_hi:[0,1]
	v_mul_f32_e32 v82, 0xbfb8aa3b, v94
	v_mul_f32_e32 v83, 0xbfb8aa3b, v95
	v_exp_f32_e32 v82, v82
	v_exp_f32_e32 v83, v83
	v_add_f32_e32 v82, 1.0, v82
	v_add_f32_e32 v83, 1.0, v83
	v_rcp_f32_e32 v82, v82
	v_rcp_f32_e32 v83, v83
	v_mul_f32_e32 v82, v94, v82
	v_mul_f32_e32 v83, v95, v83
	v_mul_f32_e32 v82, v82, v86
	v_mul_f32_e32 v83, v83, v87
	v_cvt_pk_bf16_f32 v82, v82, v83
	v_mul_f32_e32 v83, 0xbfb8aa3b, v96
	v_mul_f32_e32 v86, 0xbfb8aa3b, v97
	v_exp_f32_e32 v83, v83
	v_exp_f32_e32 v86, v86
	v_add_f32_e32 v83, 1.0, v83
	v_add_f32_e32 v86, 1.0, v86
	v_rcp_f32_e32 v83, v83
	v_rcp_f32_e32 v86, v86
	v_mul_f32_e32 v83, v96, v83
	v_mul_f32_e32 v86, v97, v86
	v_mul_f32_e32 v83, v83, v88
	v_mul_f32_e32 v86, v86, v89
	v_cvt_pk_bf16_f32 v83, v83, v86
	v_mul_f32_e32 v86, 0xbfb8aa3b, v90
	v_exp_f32_e32 v86, v86
	s_nop 0
	v_add_f32_e32 v86, 1.0, v86
	v_rcp_f32_e32 v86, v86
	s_nop 0
	v_mul_f32_e32 v86, v90, v86
	v_mul_f32_e32 v84, v86, v84
	v_mul_f32_e32 v86, 0xbfb8aa3b, v91
	v_exp_f32_e32 v86, v86
	s_nop 0
	v_add_f32_e32 v86, 1.0, v86
	v_rcp_f32_e32 v86, v86
	s_nop 0
	v_mul_f32_e32 v86, v91, v86
	v_mul_f32_e32 v85, v86, v85
	v_cvt_pk_bf16_f32 v84, v84, v85
	v_mul_f32_e32 v85, 0xbfb8aa3b, v92
	v_mul_f32_e32 v86, 0xbfb8aa3b, v93
	v_exp_f32_e32 v85, v85
	v_exp_f32_e32 v86, v86
	v_add_f32_e32 v85, 1.0, v85
	v_add_f32_e32 v86, 1.0, v86
	v_rcp_f32_e32 v85, v85
	v_rcp_f32_e32 v86, v86
	v_mul_f32_e32 v85, v92, v85
	v_mul_f32_e32 v86, v93, v86
	v_mul_f32_e32 v85, v85, v98
	v_mul_f32_e32 v86, v86, v99
	v_cvt_pk_bf16_f32 v85, v85, v86
	v_or_b32_e32 v86, 32, v151
	v_mad_i64_i32 v[86:87], s[38:39], v86, s34, v[114:115]
	v_lshl_add_u64 v[86:87], v[86:87], 0, v[116:117]
	global_store_dwordx4 v[86:87], v[82:85], off
	s_nop 1
	v_pk_mul_f32 v[82:83], v[152:153], v[68:69] op_sel_hi:[0,1]
	v_pk_mul_f32 v[68:69], v[152:153], v[66:67] op_sel_hi:[0,1]
	v_mul_f32_e32 v66, 0xbfb8aa3b, v78
	v_mul_f32_e32 v67, 0xbfb8aa3b, v79
	v_exp_f32_e32 v66, v66
	v_exp_f32_e32 v67, v67
	v_add_f32_e32 v66, 1.0, v66
	v_add_f32_e32 v67, 1.0, v67
	v_rcp_f32_e32 v66, v66
	v_rcp_f32_e32 v67, v67
	v_mul_f32_e32 v66, v78, v66
	v_mul_f32_e32 v67, v79, v67
	v_mul_f32_e32 v66, v66, v70
	v_mul_f32_e32 v67, v67, v71
	v_cvt_pk_bf16_f32 v66, v66, v67
	v_mul_f32_e32 v67, 0xbfb8aa3b, v80
	v_mul_f32_e32 v70, 0xbfb8aa3b, v81
	v_exp_f32_e32 v67, v67
	v_exp_f32_e32 v70, v70
	v_add_f32_e32 v67, 1.0, v67
	v_add_f32_e32 v70, 1.0, v70
	v_rcp_f32_e32 v67, v67
	v_rcp_f32_e32 v70, v70
	v_mul_f32_e32 v67, v80, v67
	v_mul_f32_e32 v70, v81, v70
	v_mul_f32_e32 v67, v67, v72
	v_mul_f32_e32 v70, v70, v73
	v_cvt_pk_bf16_f32 v67, v67, v70
	v_mul_f32_e32 v70, 0xbfb8aa3b, v74
	v_exp_f32_e32 v70, v70
	s_nop 0
	v_add_f32_e32 v70, 1.0, v70
	v_rcp_f32_e32 v70, v70
	s_nop 0
	v_mul_f32_e32 v70, v74, v70
	v_mul_f32_e32 v68, v70, v68
	v_mul_f32_e32 v70, 0xbfb8aa3b, v75
	v_exp_f32_e32 v70, v70
	s_nop 0
	v_add_f32_e32 v70, 1.0, v70
	v_rcp_f32_e32 v70, v70
	s_nop 0
	v_mul_f32_e32 v70, v75, v70
	v_mul_f32_e32 v69, v70, v69
	v_cvt_pk_bf16_f32 v68, v68, v69
	v_mul_f32_e32 v69, 0xbfb8aa3b, v76
	v_mul_f32_e32 v70, 0xbfb8aa3b, v77
	v_exp_f32_e32 v69, v69
	v_exp_f32_e32 v70, v70
	v_add_f32_e32 v69, 1.0, v69
	v_add_f32_e32 v70, 1.0, v70
	v_rcp_f32_e32 v69, v69
	v_rcp_f32_e32 v70, v70
	v_mul_f32_e32 v69, v76, v69
	v_mul_f32_e32 v70, v77, v70
	v_mul_f32_e32 v69, v69, v82
	v_mul_f32_e32 v70, v70, v83
	v_cvt_pk_bf16_f32 v69, v69, v70
	v_or_b32_e32 v70, 48, v151
	v_mad_i64_i32 v[70:71], s[38:39], v70, s34, v[114:115]
	v_lshl_add_u64 v[70:71], v[70:71], 0, v[116:117]
	global_store_dwordx4 v[70:71], v[66:69], off
	s_nop 1
	v_pk_mul_f32 v[66:67], v[150:151], v[52:53] op_sel_hi:[0,1]
	v_pk_mul_f32 v[52:53], v[150:151], v[50:51] op_sel_hi:[0,1]
	v_mul_f32_e32 v50, 0xbfb8aa3b, v62
	v_mul_f32_e32 v51, 0xbfb8aa3b, v63
	v_exp_f32_e32 v50, v50
	v_exp_f32_e32 v51, v51
	v_add_u32_e32 v68, 0x80, v151
	v_add_f32_e32 v50, 1.0, v50
; __device__ __forceinline__ unsigned cvt_pk_bf16(float lo, float hi) { unsigned r; asm volatile("v_cvt_pk_bf16_f32 %0, %1, %2" : "=v"(r) : "v"(lo), "v"(hi)); return r; }
; #define GAS __attribute__((address_space(1)))
; __device__ __forceinline__ float silu_mul(float g, float u) { const float e = __builtin_amdgcn_exp2f(-1.4426950408889634f * g); return g * __builtin_amdgcn_rcpf(1.0f + e) * u; }
;     __device__ __forceinline__ void operator()(const f32x4 (&acc)[2][2][4][2], const Unit& u, int wr, int wc, int fr, int fq, const float (&pre)[8]) const {
;         const int row0 = u.pm * 256 + wr * 64 + fr, col0 = u.pn * 128 + wc * 32 + 8 * fq;
; #pragma unroll
;         for (int ai = 0; ai < 2; ++ai)
; #pragma unroll
;             for (int m = 0; m < 4; ++m) {
;                 const float rsc = pre[ai * 4 + m];
;                 const f32x4 g0 = acc[ai][0][m][0] * rsc, g1 = acc[ai][0][m][1] * rsc, u0 = acc[ai][1][m][0] * rsc, u1 = acc[ai][1][m][1] * rsc;
;                 u32x4 w; w.x = cvt_pk_bf16(silu_mul(g0[0], u0[0]), silu_mul(g0[1], u0[1])); w.y = cvt_pk_bf16(silu_mul(g0[2], u0[2]), silu_mul(g0[3], u0[3]));
;                 w.z = cvt_pk_bf16(silu_mul(g1[0], u1[0]), silu_mul(g1[1], u1[1])); w.w = cvt_pk_bf16(silu_mul(g1[2], u1[2]), silu_mul(g1[3], u1[3]));
;                 *(GAS u32x4*)(O + (size_t)(row0 + ai * 128 + m * 16) * DFF + col0) = w; }
	v_add_f32_e32 v51, 1.0, v51
	v_rcp_f32_e32 v50, v50
	v_rcp_f32_e32 v51, v51
	v_mul_f32_e32 v50, v62, v50
	v_mul_f32_e32 v51, v63, v51
	v_mul_f32_e32 v50, v50, v54
	v_mul_f32_e32 v51, v51, v55
	v_cvt_pk_bf16_f32 v50, v50, v51
	v_mul_f32_e32 v51, 0xbfb8aa3b, v64
	v_mul_f32_e32 v54, 0xbfb8aa3b, v65
	v_exp_f32_e32 v51, v51
	v_exp_f32_e32 v54, v54
	v_add_f32_e32 v51, 1.0, v51
	v_add_f32_e32 v54, 1.0, v54
	v_rcp_f32_e32 v51, v51
	v_rcp_f32_e32 v54, v54
	v_mul_f32_e32 v51, v64, v51
	v_mul_f32_e32 v54, v65, v54
	v_mul_f32_e32 v51, v51, v56
	v_mul_f32_e32 v54, v54, v57
	v_cvt_pk_bf16_f32 v51, v51, v54
	v_mul_f32_e32 v54, 0xbfb8aa3b, v58
	v_exp_f32_e32 v54, v54
	s_nop 0
	v_add_f32_e32 v54, 1.0, v54
	v_rcp_f32_e32 v54, v54
	s_nop 0
	v_mul_f32_e32 v54, v58, v54
	v_mul_f32_e32 v52, v54, v52
	v_mul_f32_e32 v54, 0xbfb8aa3b, v59
	v_exp_f32_e32 v54, v54
	s_nop 0
	v_add_f32_e32 v54, 1.0, v54
	v_rcp_f32_e32 v54, v54
	s_nop 0
	v_mul_f32_e32 v54, v59, v54
	v_mul_f32_e32 v53, v54, v53
	v_cvt_pk_bf16_f32 v52, v52, v53
	v_mul_f32_e32 v53, 0xbfb8aa3b, v60
	v_mul_f32_e32 v54, 0xbfb8aa3b, v61
	v_exp_f32_e32 v53, v53
	v_exp_f32_e32 v54, v54
	v_add_f32_e32 v53, 1.0, v53
	v_add_f32_e32 v54, 1.0, v54
	v_rcp_f32_e32 v53, v53
	v_rcp_f32_e32 v54, v54
	v_mul_f32_e32 v53, v60, v53
	v_mul_f32_e32 v54, v61, v54
	v_mul_f32_e32 v53, v53, v66
	v_mul_f32_e32 v54, v54, v67
	v_cvt_pk_bf16_f32 v53, v53, v54
	v_mad_i64_i32 v[54:55], s[38:39], v68, s34, v[114:115]
	v_lshl_add_u64 v[54:55], v[54:55], 0, v[116:117]
	global_store_dwordx4 v[54:55], v[50:53], off
	s_nop 1
	v_pk_mul_f32 v[50:51], v[148:149], v[36:37] op_sel_hi:[0,1]
	v_pk_mul_f32 v[36:37], v[148:149], v[34:35] op_sel_hi:[0,1]
	v_mul_f32_e32 v34, 0xbfb8aa3b, v46
	v_mul_f32_e32 v35, 0xbfb8aa3b, v47
	v_exp_f32_e32 v34, v34
	v_exp_f32_e32 v35, v35
	v_add_f32_e32 v34, 1.0, v34
	v_add_f32_e32 v35, 1.0, v35
	v_rcp_f32_e32 v34, v34
	v_rcp_f32_e32 v35, v35
	v_mul_f32_e32 v34, v46, v34
	v_mul_f32_e32 v35, v47, v35
	v_mul_f32_e32 v34, v34, v38
	v_mul_f32_e32 v35, v35, v39
	v_cvt_pk_bf16_f32 v34, v34, v35
	v_mul_f32_e32 v35, 0xbfb8aa3b, v48
	v_mul_f32_e32 v38, 0xbfb8aa3b, v49
	v_exp_f32_e32 v35, v35
	v_exp_f32_e32 v38, v38
	v_add_f32_e32 v35, 1.0, v35
	v_add_f32_e32 v38, 1.0, v38
	v_rcp_f32_e32 v35, v35
	v_rcp_f32_e32 v38, v38
	v_mul_f32_e32 v35, v48, v35
	v_mul_f32_e32 v38, v49, v38
	v_mul_f32_e32 v35, v35, v40
	v_mul_f32_e32 v38, v38, v41
	v_cvt_pk_bf16_f32 v35, v35, v38
	v_mul_f32_e32 v38, 0xbfb8aa3b, v42
	v_exp_f32_e32 v38, v38
	s_nop 0
	v_add_f32_e32 v38, 1.0, v38
	v_rcp_f32_e32 v38, v38
	s_nop 0
	v_mul_f32_e32 v38, v42, v38
	v_mul_f32_e32 v36, v38, v36
	v_mul_f32_e32 v38, 0xbfb8aa3b, v43
	v_exp_f32_e32 v38, v38
	s_nop 0
	v_add_f32_e32 v38, 1.0, v38
	v_rcp_f32_e32 v38, v38
	s_nop 0
	v_mul_f32_e32 v38, v43, v38
	v_mul_f32_e32 v37, v38, v37
	v_cvt_pk_bf16_f32 v36, v36, v37
	v_mul_f32_e32 v37, 0xbfb8aa3b, v44
	v_mul_f32_e32 v38, 0xbfb8aa3b, v45
	v_exp_f32_e32 v37, v37
	v_exp_f32_e32 v38, v38
	v_add_f32_e32 v37, 1.0, v37
	v_add_f32_e32 v38, 1.0, v38
	v_rcp_f32_e32 v37, v37
	v_rcp_f32_e32 v38, v38
	v_mul_f32_e32 v37, v44, v37
	v_mul_f32_e32 v38, v45, v38
	v_mul_f32_e32 v37, v37, v50
	v_mul_f32_e32 v38, v38, v51
	v_cvt_pk_bf16_f32 v37, v37, v38
	v_add_u32_e32 v38, 0x90, v151
	v_mad_i64_i32 v[38:39], s[38:39], v38, s34, v[114:115]
	v_lshl_add_u64 v[38:39], v[38:39], 0, v[116:117]
	global_store_dwordx4 v[38:39], v[34:37], off
	s_nop 1
	v_pk_mul_f32 v[34:35], v[146:147], v[18:19] op_sel_hi:[0,1]
	v_pk_mul_f32 v[18:19], v[146:147], v[16:17] op_sel_hi:[0,1]
	v_mul_f32_e32 v16, 0xbfb8aa3b, v28
	v_mul_f32_e32 v17, 0xbfb8aa3b, v29
	v_exp_f32_e32 v16, v16
	v_exp_f32_e32 v17, v17
	v_add_f32_e32 v16, 1.0, v16
	v_add_f32_e32 v17, 1.0, v17
	v_rcp_f32_e32 v16, v16
	v_rcp_f32_e32 v17, v17
	v_mul_f32_e32 v16, v28, v16
	v_mul_f32_e32 v17, v29, v17
	v_mul_f32_e32 v16, v16, v20
	v_mul_f32_e32 v17, v17, v21
	v_cvt_pk_bf16_f32 v16, v16, v17
	v_mul_f32_e32 v17, 0xbfb8aa3b, v30
	v_mul_f32_e32 v20, 0xbfb8aa3b, v31
	v_exp_f32_e32 v17, v17
	v_exp_f32_e32 v20, v20
	v_add_f32_e32 v17, 1.0, v17
	v_add_f32_e32 v20, 1.0, v20
	v_rcp_f32_e32 v17, v17
	v_rcp_f32_e32 v20, v20
	v_mul_f32_e32 v17, v30, v17
	v_mul_f32_e32 v20, v31, v20
	v_mul_f32_e32 v17, v17, v22
	v_mul_f32_e32 v20, v20, v23
	v_cvt_pk_bf16_f32 v17, v17, v20
	v_mul_f32_e32 v20, 0xbfb8aa3b, v24
	v_exp_f32_e32 v20, v20
	s_nop 0
	v_add_f32_e32 v20, 1.0, v20
	v_rcp_f32_e32 v20, v20
	s_nop 0
	v_mul_f32_e32 v20, v24, v20
	v_mul_f32_e32 v18, v20, v18
	v_mul_f32_e32 v20, 0xbfb8aa3b, v25
	v_exp_f32_e32 v20, v20
	s_nop 0
	v_add_f32_e32 v20, 1.0, v20
	v_rcp_f32_e32 v20, v20
	s_nop 0
	v_mul_f32_e32 v20, v25, v20
	v_mul_f32_e32 v19, v20, v19
	v_cvt_pk_bf16_f32 v18, v18, v19
	v_mul_f32_e32 v19, 0xbfb8aa3b, v26
	v_mul_f32_e32 v20, 0xbfb8aa3b, v27
	v_exp_f32_e32 v19, v19
	v_exp_f32_e32 v20, v20
	v_add_f32_e32 v19, 1.0, v19
	v_add_f32_e32 v20, 1.0, v20
	v_rcp_f32_e32 v19, v19
	v_rcp_f32_e32 v20, v20
	v_mul_f32_e32 v19, v26, v19
	v_mul_f32_e32 v20, v27, v20
	v_mul_f32_e32 v19, v19, v34
	v_mul_f32_e32 v20, v20, v35
	v_cvt_pk_bf16_f32 v19, v19, v20
	v_add_u32_e32 v20, 0xa0, v151
	v_mad_i64_i32 v[20:21], s[38:39], v20, s34, v[114:115]
	v_lshl_add_u64 v[20:21], v[20:21], 0, v[116:117]
	global_store_dwordx4 v[20:21], v[16:19], off
	s_nop 1
	v_pk_mul_f32 v[16:17], v[144:145], v[2:3] op_sel_hi:[0,1]
	v_pk_mul_f32 v[2:3], v[144:145], v[0:1] op_sel_hi:[0,1]
	v_mul_f32_e32 v0, 0xbfb8aa3b, v12
	v_mul_f32_e32 v1, 0xbfb8aa3b, v13
	v_exp_f32_e32 v0, v0
	v_exp_f32_e32 v1, v1
	v_add_f32_e32 v0, 1.0, v0
	v_add_f32_e32 v1, 1.0, v1
	v_rcp_f32_e32 v0, v0
	v_rcp_f32_e32 v1, v1
	v_mul_f32_e32 v0, v12, v0
	v_mul_f32_e32 v1, v13, v1
	v_mul_f32_e32 v0, v0, v4
	v_mul_f32_e32 v1, v1, v5
	v_cvt_pk_bf16_f32 v0, v0, v1
	v_mul_f32_e32 v1, 0xbfb8aa3b, v14
	v_mul_f32_e32 v4, 0xbfb8aa3b, v15
	v_exp_f32_e32 v1, v1
	v_exp_f32_e32 v4, v4
	v_add_f32_e32 v1, 1.0, v1
	v_add_f32_e32 v4, 1.0, v4
	v_rcp_f32_e32 v1, v1
	v_rcp_f32_e32 v4, v4
	v_mul_f32_e32 v1, v14, v1
	v_mul_f32_e32 v4, v15, v4
	v_mul_f32_e32 v1, v1, v6
	v_mul_f32_e32 v4, v4, v7
	v_cvt_pk_bf16_f32 v1, v1, v4
	v_mul_f32_e32 v4, 0xbfb8aa3b, v8
	v_exp_f32_e32 v4, v4
	s_nop 0
	v_add_f32_e32 v4, 1.0, v4
	v_rcp_f32_e32 v4, v4
	s_nop 0
	v_mul_f32_e32 v4, v8, v4
	v_mul_f32_e32 v2, v4, v2
	v_mul_f32_e32 v4, 0xbfb8aa3b, v9
	v_exp_f32_e32 v4, v4
	s_nop 0
	v_add_f32_e32 v4, 1.0, v4
	v_rcp_f32_e32 v4, v4
	s_nop 0
	v_mul_f32_e32 v4, v9, v4
	v_mul_f32_e32 v3, v4, v3
	v_cvt_pk_bf16_f32 v2, v2, v3
	v_mul_f32_e32 v3, 0xbfb8aa3b, v10
	v_mul_f32_e32 v4, 0xbfb8aa3b, v11
	v_exp_f32_e32 v3, v3
	v_exp_f32_e32 v4, v4
	v_add_f32_e32 v3, 1.0, v3
	v_add_f32_e32 v4, 1.0, v4
	v_rcp_f32_e32 v3, v3
	v_rcp_f32_e32 v4, v4
	v_mul_f32_e32 v3, v10, v3
	v_mul_f32_e32 v4, v11, v4
	v_mul_f32_e32 v3, v3, v16
	v_mul_f32_e32 v4, v4, v17
	v_cvt_pk_bf16_f32 v3, v3, v4
	v_add_u32_e32 v4, 0xb0, v151
	v_mad_i64_i32 v[4:5], s[38:39], v4, s34, v[114:115]
	v_lshl_add_u64 v[4:5], v[4:5], 0, v[116:117]
	global_store_dwordx4 v[4:5], v[0:3], off
	s_cbranch_vccnz .LBB0_439
; #define PG8_BAR __builtin_amdgcn_s_barrier()
; #define GAS __attribute__((address_space(1)))
; template <class Epi, class Sched, bool ALIGN_EPI = false, bool SP2 = false>
; __device__ __forceinline__ void gemm_phase(PG8_LAS unsigned char* lds, const Gemm g, const Sched& S, const Epi& E) {
;     ...
;         cur = nxt; cA = nA; cB = nB; ++ui;
;         if constexpr (Epi::PREFETCH) E.prefetch(cur, wr, fr, epre);
;         if constexpr (ALIGN_EPI) { if (wr == 1) PG8_BAR; }
;     __device__ __forceinline__ void prefetch(const Unit& u, int wr, int fr, float (&pre)[8]) const {
; #pragma unroll
;         for (int i = 0; i < 8; ++i) pre[i] = *(const GAS float*)(rs + u.pm * 256 + wr * 64 + fr + (i >> 2) * 128 + (i & 3) * 16);
;     }
	s_lshl_b32 s38, s42, 8
	s_ashr_i32 s39, s38, 31
	v_lshl_add_u64 v[0:1], s[38:39], 2, v[138:139]
	global_load_dword v158, v[0:1], off
	global_load_dword v156, v[0:1], off offset:64
	global_load_dword v154, v[0:1], off offset:128
	global_load_dword v152, v[0:1], off offset:192
	global_load_dword v150, v[0:1], off offset:512
	global_load_dword v148, v[0:1], off offset:576
	global_load_dword v146, v[0:1], off offset:640
	global_load_dword v144, v[0:1], off offset:704
	s_andn2_b64 vcc, exec, s[2:3]
	s_cbranch_vccnz .LBB0_438
	s_barrier
	s_branch .LBB0_438

; #define PG8_STAGE(bufoff, gbase, voff) do { _Pragma("unroll") for (int _i = 0; _i < 2; ++_i) \
;         __builtin_amdgcn_global_load_lds((const unsigned*)((const char*)(gbase) + (voff)[_i]), (PG8_LAS unsigned*)(lds + (bufoff) + ldsw + _i * 8192), 16, 0, 0); } while (0)
; #define PG8_BAR __builtin_amdgcn_s_barrier()
; template <class Epi, class Sched, bool ALIGN_EPI = false, bool SP2 = false>
; __device__ __forceinline__ void gemm_phase(PG8_LAS unsigned char* lds, const Gemm g, const Sched& S, const Epi& E) {
;     ...
;     for (int i = 0; i < 2; ++i) { int R, C; stage_rc(tid * 16 + i * 8192, R, C); const int Rb = Epi::PERM ? ((R & ~31) + perm32(R & 31)) : R;
;         voffA[i] = (unsigned)(R * K + C) * 2u; voffB[i] = (unsigned)(Rb * K + C) * 2u; }
;     const size_t kstep = (size_t)(BK * 2);
;     const size_t hstep = (size_t)HALF * K * 2;
;     const size_t tstep = 2 * hstep;
;     const unsigned ldsw = (unsigned)wid * 1024u;
;     const int aoff = lds_byte(wr * 64 + fr, fq * 8), boff = lds_byte(wc * 32 + fr, fq * 8);
;     ...
;     const char* cA = (const char*)g.A + (size_t)cur.pm * tstep; const char* cB = (const char*)g.Bt + (size_t)cur.pn * tstep;
;     S.a_ready(cur);
;     float epre[8];
;     if constexpr (Epi::PREFETCH) E.prefetch(cur, wr, fr, epre);
;     if constexpr (SP2) {
;         PG8_STAGE(PG8_SB(0, 0), cB, voffB); PG8_STAGE(PG8_SB(0, 1), cB + hstep, voffB); PG8_STAGE(PG8_SA(0, 0), cA, voffA); PG8_STAGE(PG8_SA(0, 1), cA + hstep, voffA);
;         if (wr == 1) PG8_BAR;
.LBB0_535:
	s_andn2_b64 vcc, exec, s[2:3]
	s_cbranch_vccnz .LBB0_569
	v_bfe_i32 v2, v18, 27, 1
	v_lshlrev_b32_e32 v0, 4, v18
	v_lshrrev_b32_e32 v2, 22, v2
	v_add_u32_e32 v2, v0, v2
	v_and_b32_e32 v2, 0xfffffc00, v2
	v_sub_u32_e32 v2, v0, v2
	v_ashrrev_i32_e32 v1, 31, v18
	v_lshrrev_b32_e32 v3, 4, v2
	v_lshrrev_b32_e32 v1, 26, v1
	v_bitop3_b32 v2, v3, v2, 32 bitop3:0x6c
	v_add_u32_e32 v1, v18, v1
	v_ashrrev_i32_e32 v4, 31, v2
	v_ashrrev_i32_e32 v1, 6, v1
	v_lshrrev_b32_e32 v4, 26, v4
	v_lshlrev_b32_e32 v3, 3, v1
	v_add_u32_e32 v4, v2, v4
	v_and_b32_e32 v3, -16, v3
	v_ashrrev_i32_e32 v5, 6, v4
	v_lshlrev_b32_e32 v1, 5, v1
	v_add_u32_e32 v3, v5, v3
	v_and_b32_e32 v12, 32, v1
	v_and_b32_e32 v1, 0xc0, v4
	v_sub_u32_e32 v1, v2, v1
	v_lshlrev_b32_e32 v2, 1, v3
	v_lshrrev_b32_e32 v4, 2, v3
	v_and_b32_e32 v5, 3, v5
	s_mov_b32 s3, 0x7fffffe0
	v_ashrrev_i16_sdwa v1, v189, sext(v1) dst_sel:DWORD dst_unused:UNUSED_PAD src0_sel:DWORD src1_sel:BYTE_0
	v_and_b32_e32 v2, 24, v2
	v_and_b32_e32 v4, 4, v4
	v_and_or_b32 v5, v3, s3, v5
	v_bfe_i32 v13, v1, 0, 16
	v_or3_b32 v2, v5, v4, v2
	v_add_u32_e32 v1, v12, v13
	v_mul_lo_u32 v14, v3, s84
	v_mul_lo_u32 v2, v2, s84
	v_add_u32_e32 v0, 0x2000, v0
	v_add_lshl_u32 v130, v1, v14, 1
	v_add_lshl_u32 v132, v2, v1, 1
	v_ashrrev_i32_e32 v1, 31, v0
	v_lshrrev_b32_e32 v1, 22, v1
	v_add_u32_e32 v1, v0, v1
	v_ashrrev_i32_e32 v1, 10, v1
	v_mul_i32_i24_e32 v2, 0x400, v1
	v_sub_u32_e32 v0, v0, v2
	v_lshrrev_b32_e32 v2, 4, v0
	v_bitop3_b32 v0, v2, v0, 32 bitop3:0x6c
	v_ashrrev_i32_e32 v3, 31, v0
	v_lshrrev_b32_e32 v3, 26, v3
	v_lshlrev_b32_e32 v2, 3, v1
	v_add_u32_e32 v3, v0, v3
	v_and_b32_e32 v2, -16, v2
	v_ashrrev_i32_e32 v4, 6, v3
	s_ashr_i32 s2, s40, 6
	v_add_u32_e32 v2, v4, v2
	v_lshlrev_b32_e32 v1, 5, v1
	v_and_b32_e32 v4, 3, v4
	v_and_b32_e32 v15, 32, v1
	v_and_b32_e32 v1, 0xc0, v3
	v_and_or_b32 v4, v2, s3, v4
	s_ashr_i32 s3, s40, 8
	s_lshl_b32 s51, s2, 10
	s_mul_i32 s5, s86, s50
	v_readlane_b32 s42, v254, 28
	v_sub_u32_e32 v0, v0, v1
	v_lshlrev_b32_e32 v1, 1, v2
	v_lshrrev_b32_e32 v3, 2, v2
	s_mul_hi_i32 s4, s86, s50
	v_readlane_b32 s43, v254, 29
	s_add_u32 s44, s42, s5
	v_ashrrev_i16_sdwa v0, v189, sext(v0) dst_sel:DWORD dst_unused:UNUSED_PAD src0_sel:DWORD src1_sel:BYTE_0
	v_and_b32_e32 v1, 24, v1
	v_and_b32_e32 v3, 4, v3
	s_addc_u32 s45, s43, s4
	s_add_i32 s78, s51, 0
	v_bfe_i32 v16, v0, 0, 16
	v_or3_b32 v1, v4, v3, v1
	s_add_i32 m0, s78, 0x10000
	v_add_u32_e32 v0, v15, v16
	v_mul_lo_u32 v1, v1, s84
	global_load_lds_dwordx4 v132, s[44:45]
	s_add_i32 m0, s78, 0x12000
	v_add_lshl_u32 v136, v1, v0, 1
	s_add_u32 s4, s44, s8
	global_load_lds_dwordx4 v136, s[44:45]
	s_addc_u32 s5, s45, 0
	s_add_i32 m0, s78, 0x14000
	s_mul_i32 s39, s86, s90
	global_load_lds_dwordx4 v132, s[4:5]
	s_add_i32 m0, s78, 0x16000
	s_mul_hi_i32 s38, s86, s90
	s_add_u32 s46, s6, s39
	v_mov_b32_e32 v133, v32
	v_mov_b32_e32 v137, v32
	s_addc_u32 s47, s7, s38
	s_add_i32 s79, s78, 0x2000
	v_mul_lo_u32 v17, v2, s84
	v_lshl_add_u64 v[4:5], s[4:5], 0, v[132:133]
	v_lshl_add_u64 v[6:7], s[4:5], 0, v[136:137]
	global_load_lds_dwordx4 v136, s[4:5]
	s_mov_b32 m0, s78
	s_add_u32 s4, s46, 0x4000
	v_add_lshl_u32 v134, v0, v17, 1
	s_mov_b32 s100, 0x8000
	s_mov_b32 s101, 0
	v_and_b32_e32 v242, 63, v186
	v_lshlrev_b32_e32 v242, 4, v242
	v_lshrrev_b32_e32 v243, 4, v242
	v_and_b32_e32 v243, 32, v243
	v_xor_b32_e32 v242, v242, v243
	v_lshrrev_b32_e32 v243, 6, v242
	v_and_b32_e32 v242, 63, v242
	v_lshl_add_u32 v242, v243, 7, v242
	v_lshrrev_b32_e32 v243, 6, v186
	v_and_b32_e32 v244, 1, v243
	v_lshl_add_u32 v242, v244, 6, v242
	v_lshrrev_b32_e32 v243, 1, v243
	v_lshl_add_u32 v130, v243, 11, v242
	v_add_u32_e32 v134, 0x2000, v130
	global_load_lds_dwordx4 v130, s[46:47]
	s_mov_b32 m0, s79
	s_addc_u32 s5, s47, 0
	s_add_i32 s80, s78, 0x4000
	global_load_lds_dwordx4 v134, s[46:47]
	s_mov_b32 m0, s80
	s_add_i32 s81, s78, 0x6000
	global_load_lds_dwordx4 v130, s[4:5]
	s_mov_b32 m0, s81
	v_mov_b32_e32 v131, v32
	global_load_lds_dwordx4 v134, s[4:5]
	v_mov_b32_e32 v135, v32
	s_cmp_eq_u32 s3, 1
	v_lshl_add_u64 v[0:1], s[44:45], 0, v[132:133]
	v_lshl_add_u64 v[2:3], s[44:45], 0, v[136:137]
	v_lshl_add_u64 v[8:9], s[46:47], 0, v[130:131]
	v_lshl_add_u64 v[10:11], s[46:47], 0, v[134:135]
	s_cselect_b64 s[38:39], -1, 0
	s_cmp_lg_u32 s3, 1
	s_cbranch_scc1 .LBB0_538
	s_barrier
; #define PG8_STAGE(bufoff, gbase, voff) do { _Pragma("unroll") for (int _i = 0; _i < 2; ++_i) \
;         __builtin_amdgcn_global_load_lds((const unsigned*)((const char*)(gbase) + (voff)[_i]), (PG8_LAS unsigned*)(lds + (bufoff) + ldsw + _i * 8192), 16, 0, 0); } while (0)
; #define PG8_WAIT_V(n) asm volatile("s_waitcnt vmcnt(" #n ")" ::: "memory")
; #define PG8_BAR __builtin_amdgcn_s_barrier()
;     __host__ __device__ bool next(int i, Unit& u) const {
;         if (i >= ni) return false;
;         const long L = (long)(i + i0) * G + c; if (L >= nwg) return false;
;         int wgid = (int)L; { const int q = nwg / NXCD, r = nwg % NXCD, xcd = wgid % NXCD, off = wgid / NXCD; wgid = (xcd < r ? xcd * (q + 1) : r * (q + 1) + (xcd - r) * q) + off; }
;         const int nig = WGM * nN, gid = wgid / nig, fm = gid * WGM, gsz = (nM - fm) < WGM ? (nM - fm) : WGM;
;         u.pm = fm + ((wgid % nig) % gsz); u.pn = (wgid % nig) / gsz; return true;
; template <class Epi, class Sched, bool ALIGN_EPI = false, bool SP2 = false>
; __device__ __forceinline__ void gemm_phase(PG8_LAS unsigned char* lds, const Gemm g, const Sched& S, const Epi& E) {
;     ...
;         PG8_WAIT_V(2); PG8_BAR;
;         PG8_STAGE(PG8_SB(1, 0), cB + kstep, voffB); PG8_STAGE(PG8_SA(1, 0), cA + kstep, voffA); PG8_STAGE(PG8_SB(1, 1), cB + hstep + kstep, voffB);
;         PG8_WAIT_V(6); PG8_BAR;
;     } else {
;         PG8_STAGE(PG8_SB(0, 0), cB, voffB); PG8_STAGE(PG8_SA(0, 0), cA, voffA); PG8_STAGE(PG8_SB(0, 1), cB + hstep, voffB); PG8_STAGE(PG8_SA(0, 1), cA + hstep, voffA);
;         if (wr == 1) PG8_BAR;
;         PG8_WAIT_V(4); PG8_BAR;
;         PG8_STAGE(PG8_SB(1, 0), cB + kstep, voffB); PG8_STAGE(PG8_SA(1, 0), cA + kstep, voffA); PG8_STAGE(PG8_SB(1, 1), cB + hstep + kstep, voffB);
;         PG8_WAIT_V(6); PG8_BAR;
;     }
;     for (;;) {
;         const bool has_next = S.next(ui + 1, nxt);
;         const char* nA = has_next ? (const char*)g.A + (size_t)nxt.pm * tstep : cA; const char* nB = has_next ? (const char*)g.Bt + (size_t)nxt.pn * tstep : cB;
.LBB0_538:
	s_add_i32 m0, s78, 0x18000
	v_lshl_add_u64 v[0:1], v[0:1], 0, s[34:35]
	s_waitcnt vmcnt(2)
	s_barrier
	global_load_lds_dwordx4 v[0:1], off
	v_lshl_add_u64 v[0:1], v[2:3], 0, s[34:35]
	s_add_i32 m0, s78, 0x1a000
	s_add_i32 s83, s78, 0x8000
	global_load_lds_dwordx4 v[0:1], off
	v_lshl_add_u64 v[0:1], v[8:9], 0, s[100:101]
	s_mov_b32 m0, s83
	s_add_i32 s84, s78, 0xa000
	global_load_lds_dwordx4 v[0:1], off
	v_lshl_add_u64 v[0:1], v[10:11], 0, s[100:101]
	s_mov_b32 m0, s84
	v_bfe_u32 v19, v18, 4, 2
	global_load_lds_dwordx4 v[0:1], off
	s_add_i32 m0, s78, 0x1c000
	v_lshl_add_u64 v[0:1], v[4:5], 0, s[34:35]
	global_load_lds_dwordx4 v[0:1], off
	v_lshl_add_u64 v[0:1], v[6:7], 0, s[34:35]
	s_add_i32 m0, s78, 0x1e000
	v_and_b32_e32 v20, 15, v18
	global_load_lds_dwordx4 v[0:1], off
	v_lshlrev_b32_e32 v22, 4, v19
	v_lshlrev_b32_e32 v18, 2, v18
	s_and_b32 s82, s2, 3
	v_lshl_or_b32 v33, s3, 6, v20
	v_lshl_or_b32 v20, v20, 6, v22
	s_lshl_b32 s2, s3, 13
	v_and_b32_e32 v18, 32, v18
	v_bitop3_b32 v22, v20, s2, v18 bitop3:0xde
	s_lshl_b32 s2, s82, 12
	s_add_i32 s87, s85, -2
	s_cmpk_lt_u32 s40, 0x100
	s_mul_i32 s4, s36, 3
	s_cselect_b64 s[40:41], -1, 0
	s_add_u32 s4, s4, s53
	s_mul_hi_u32 s5, s36, 3
	s_addc_u32 s5, s5, s0
	s_ashr_i32 s0, s4, 31
	s_lshr_b32 s0, s0, 29
	s_add_i32 s0, s4, s0
	v_cmp_lt_i64_e64 s[48:49], s[4:5], v[168:169]
	s_ashr_i32 s5, s0, 3
	s_and_b32 s0, s0, -8
	s_sub_i32 s0, s4, s0
	s_lshl_b32 s4, s0, 7
	s_cmp_lt_i32 s0, 0
	s_mulk_i32 s0, 0x81
	s_cselect_b32 s0, s0, s4
	s_add_i32 s0, s0, s5
	s_ashr_i32 s4, s0, 31
	s_lshr_b32 s4, s4, 27
	s_add_i32 s4, s0, s4
	s_ashr_i32 s5, s4, 5
	s_lshl_b32 s5, s5, 3
	s_sub_i32 s42, 0x100, s5
	s_min_i32 s42, s42, 8
	s_abs_i32 s61, s42
	v_cvt_f32_u32_e32 v0, s61
	s_sub_i32 s72, 0, s61
	s_andn2_b32 s4, s4, 31
	s_sub_i32 s0, s0, s4
	v_rcp_iflag_f32_e32 v0, v0
	s_abs_i32 s43, s0
	s_xor_b32 s4, s0, s42
	s_ashr_i32 s4, s4, 31
	v_mul_f32_e32 v0, 0x4f7ffffe, v0
	v_cvt_u32_f32_e32 v0, v0
	v_mov_b32_e32 v1, v32
	s_waitcnt vmcnt(6)
	v_lshlrev_b32_e32 v21, 3, v19
	v_readfirstlane_b32 s73, v0
	s_mul_i32 s72, s72, s73
	s_mul_hi_u32 s72, s73, s72
	s_add_i32 s73, s73, s72
	s_mul_hi_u32 s72, s43, s73
	s_mul_i32 s73, s72, s61
	s_sub_i32 s43, s43, s73
	s_add_i32 s73, s72, 1
	s_sub_i32 s76, s43, s61
	s_cmp_ge_u32 s43, s61
	s_cselect_b32 s72, s73, s72
	s_cselect_b32 s43, s76, s43
	s_add_i32 s73, s72, 1
	s_cmp_ge_u32 s43, s61
	s_cselect_b32 s43, s73, s72
	s_xor_b32 s43, s43, s4
	v_add_u32_e32 v0, v17, v15
	s_sub_i32 s88, s43, s4
	v_add_lshl_u32 v0, v0, v16, 1
	s_mul_i32 s4, s88, s42
	v_lshl_add_u64 v[138:139], s[8:9], 0, v[0:1]
	v_add_u32_e32 v0, v14, v12
	s_sub_i32 s0, s0, s4
	v_add_lshl_u32 v0, v0, v13, 1
	s_waitcnt vmcnt(0)
	v_bitop3_b32 v146, v20, s2, v18 bitop3:0xde
	v_lshl_or_b32 v147, s82, 5, v21
	v_cmp_eq_u32_e64 s[2:3], 0, v19
	s_add_i32 s89, s5, s0
	v_lshl_add_u64 v[140:141], s[8:9], 0, v[0:1]
	v_add_u32_e32 v140, 0x4000, v130
	v_mov_b32_e32 v141, v32
	v_add_u32_e32 v138, 0x4000, v134
	v_mov_b32_e32 v139, v32
	v_add_u32_e32 v148, 0, v22
	s_barrier
	s_branch .LBB0_541

; #define PG8_STAGE(bufoff, gbase, voff) do { _Pragma("unroll") for (int _i = 0; _i < 2; ++_i) \
;         __builtin_amdgcn_global_load_lds((const unsigned*)((const char*)(gbase) + (voff)[_i]), (PG8_LAS unsigned*)(lds + (bufoff) + ldsw + _i * 8192), 16, 0, 0); } while (0)
; #define PG8_LDA(dst, b, h) do { _Pragma("unroll") for (int m = 0; m < 4; ++m) _Pragma("unroll") for (int k = 0; k < 2; ++k) dst[m][k] = *(const PG8_LAS bf16x8*)(lds + PG8_SA(b, h) + aoff + m * 2048 + k * 1024); } while (0)
; #define PG8_LDB(dst, b, h) do { _Pragma("unroll") for (int n = 0; n < 2; ++n) _Pragma("unroll") for (int k = 0; k < 2; ++k) dst[n][k] = *(const PG8_LAS bf16x8*)(lds + PG8_SB(b, h) + boff + n * 2048 + k * 1024); } while (0)
; #define PG8_MMA(ai, bj, At, Bt) do { __builtin_amdgcn_s_setprio(1); _Pragma("unroll") for (int m = 0; m < 4; ++m) _Pragma("unroll") for (int n = 0; n < 2; ++n) _Pragma("unroll") for (int k = 0; k < 2; ++k) \
;         acc[ai][bj][m][n] = __builtin_amdgcn_mfma_f32_16x16x32_bf16(Bt[n][k], At[m][k], acc[ai][bj][m][n], 0, 0, 0); __builtin_amdgcn_s_setprio(0); } while (0)
; #define PG8_WAIT_V(n) asm volatile("s_waitcnt vmcnt(" #n ")" ::: "memory")
; template <class Epi, class Sched, bool ALIGN_EPI = false, bool SP2 = false>
; __device__ __forceinline__ void gemm_phase(PG8_LAS unsigned char* lds, const Gemm g, const Sched& S, const Epi& E) {
;     ...
;         for (int t = 0; t < nt; t += 2) {
;             const bool last = (t == nt - 2);
;             const char* a1 = cA + (size_t)(t + 1) * kstep;
;             const char* a2 = last ? nA : cA + (size_t)(t + 2) * kstep; const char* b2 = last ? nB : cB + (size_t)(t + 2) * kstep;
;             const char* a3 = a2 + kstep; const char* b3 = b2 + kstep;
;             if (last && has_next) S.a_ready(nxt);
;             if constexpr (SP2) {
;             PG8_LDB(B0, 0, 0); PG8_LDB(B1, 0, 1); PG8_SCHED; PG8_LDA(At, 0, 0); PG8_STAGE(PG8_SA(1, 1), a1 + hstep, voffA);
;             PG8_WAIT_V(8); PG8_WAIT_L(0); PG8_BAR; PG8_MMA(0, 0, At, B0); PG8_MMA(0, 1, At, B1); PG8_BAR; PG8_SCHED;
;     ...
; #pragma unroll
;         for (int a = 0; a < 2; ++a)
; #pragma unroll
;             for (int b = 0; b < 2; ++b)
; #pragma unroll
;                 for (int m = 0; m < 4; ++m)
; #pragma unroll
;                     for (int n = 0; n < 2; ++n) acc[a][b][m][n] = (f32x4){0.f, 0.f, 0.f, 0.f};
;         cur = nxt; cA = nA; cB = nB; ++ui;
.LBB0_545:
	s_add_u32 s0, s44, 0x100
	s_addc_u32 s9, s45, 0
	s_add_u32 s44, s46, 0x8000
	v_mov_b32_e32 v0, 0
	s_addc_u32 s45, s47, 0
	s_mov_b32 s46, 0
	v_mov_b32_e32 v1, v0
	v_mov_b32_e32 v2, v0
	v_mov_b32_e32 v3, v0
	v_mov_b32_e32 v4, v0
	s_waitcnt lgkmcnt(0)
	v_mov_b32_e32 v5, v0
	v_mov_b32_e32 v6, v0
	v_mov_b32_e32 v7, v0
	v_mov_b32_e32 v16, v0
	v_mov_b32_e32 v17, v0
	v_mov_b32_e32 v18, v0
	v_mov_b32_e32 v19, v0
	v_mov_b32_e32 v20, v0
	v_mov_b32_e32 v21, v0
	v_mov_b32_e32 v22, v0
	v_mov_b32_e32 v23, v0
	v_mov_b32_e32 v34, v0
	v_mov_b32_e32 v35, v0
	v_mov_b32_e32 v36, v0
	v_mov_b32_e32 v37, v0
	v_mov_b32_e32 v38, v0
	v_mov_b32_e32 v39, v0
	v_mov_b32_e32 v40, v0
	v_mov_b32_e32 v41, v0
	v_mov_b32_e32 v50, v0
	v_mov_b32_e32 v51, v0
	v_mov_b32_e32 v52, v0
	v_mov_b32_e32 v53, v0
	v_mov_b32_e32 v54, v0
	v_mov_b32_e32 v55, v0
	v_mov_b32_e32 v56, v0
	v_mov_b32_e32 v57, v0
	v_mov_b32_e32 v8, v0
	v_mov_b32_e32 v9, v0
	v_mov_b32_e32 v10, v0
	v_mov_b32_e32 v11, v0
	v_mov_b32_e32 v12, v0
	v_mov_b32_e32 v13, v0
	v_mov_b32_e32 v14, v0
	v_mov_b32_e32 v15, v0
	v_mov_b32_e32 v24, v0
	v_mov_b32_e32 v25, v0
	v_mov_b32_e32 v26, v0
	v_mov_b32_e32 v27, v0
	v_mov_b32_e32 v28, v0
	v_mov_b32_e32 v29, v0
	v_mov_b32_e32 v30, v0
	v_mov_b32_e32 v31, v0
	v_mov_b32_e32 v42, v0
	v_mov_b32_e32 v43, v0
	v_mov_b32_e32 v44, v0
	v_mov_b32_e32 v45, v0
	v_mov_b32_e32 v46, v0
	v_mov_b32_e32 v47, v0
	v_mov_b32_e32 v48, v0
	v_mov_b32_e32 v49, v0
	v_mov_b32_e32 v58, v0
	v_mov_b32_e32 v59, v0
	v_mov_b32_e32 v60, v0
	v_mov_b32_e32 v61, v0
	v_mov_b32_e32 v62, v0
	v_mov_b32_e32 v63, v0
	v_mov_b32_e32 v64, v0
	v_mov_b32_e32 v65, v0
	v_mov_b32_e32 v66, v0
	v_mov_b32_e32 v67, v0
	v_mov_b32_e32 v68, v0
	v_mov_b32_e32 v69, v0
	v_mov_b32_e32 v70, v0
	v_mov_b32_e32 v71, v0
	v_mov_b32_e32 v72, v0
	v_mov_b32_e32 v73, v0
	v_mov_b32_e32 v82, v0
	v_mov_b32_e32 v83, v0
	v_mov_b32_e32 v84, v0
	v_mov_b32_e32 v85, v0
	v_mov_b32_e32 v86, v0
	v_mov_b32_e32 v87, v0
	v_mov_b32_e32 v88, v0
	v_mov_b32_e32 v89, v0
	v_mov_b32_e32 v98, v0
	v_mov_b32_e32 v99, v0
	v_mov_b32_e32 v100, v0
	v_mov_b32_e32 v101, v0
	v_mov_b32_e32 v102, v0
	v_mov_b32_e32 v103, v0
	v_mov_b32_e32 v104, v0
	v_mov_b32_e32 v105, v0
	v_mov_b32_e32 v114, v0
	v_mov_b32_e32 v115, v0
	v_mov_b32_e32 v116, v0
	v_mov_b32_e32 v117, v0
	v_mov_b32_e32 v118, v0
	v_mov_b32_e32 v119, v0
	v_mov_b32_e32 v120, v0
	v_mov_b32_e32 v121, v0
	v_mov_b32_e32 v74, v0
	v_mov_b32_e32 v75, v0
	v_mov_b32_e32 v76, v0
	v_mov_b32_e32 v77, v0
	v_mov_b32_e32 v78, v0
	v_mov_b32_e32 v79, v0
	v_mov_b32_e32 v80, v0
	v_mov_b32_e32 v81, v0
	v_mov_b32_e32 v90, v0
	v_mov_b32_e32 v91, v0
	v_mov_b32_e32 v92, v0
	v_mov_b32_e32 v93, v0
	v_mov_b32_e32 v94, v0
	v_mov_b32_e32 v95, v0
	v_mov_b32_e32 v96, v0
	v_mov_b32_e32 v97, v0
	v_mov_b32_e32 v106, v0
	v_mov_b32_e32 v107, v0
	v_mov_b32_e32 v108, v0
	v_mov_b32_e32 v109, v0
	v_mov_b32_e32 v110, v0
	v_mov_b32_e32 v111, v0
	v_mov_b32_e32 v112, v0
	v_mov_b32_e32 v113, v0
	v_mov_b32_e32 v122, v0
	v_mov_b32_e32 v123, v0
	v_mov_b32_e32 v124, v0
	v_mov_b32_e32 v125, v0
	v_mov_b32_e32 v126, v0
	v_mov_b32_e32 v127, v0
	v_mov_b32_e32 v128, v0
	v_mov_b32_e32 v129, v0
.LBB0_546:
	s_add_i32 s48, s46, 2
	s_add_u32 s49, s44, 0x8000
	s_addc_u32 s47, s45, 0
	s_add_i32 s61, 0, 0x10000
	s_cmp_eq_u32 s87, s46
	s_cselect_b32 s47, s43, s47
	s_cselect_b32 s46, s42, s49
	v_add_u32_e32 v149, s61, v146
	s_cselect_b32 s93, s77, s9
	s_cselect_b32 s92, s76, s0
	s_add_i32 s49, 0, 0x14000
	ds_read_b128 v[142:145], v149
	ds_read_b128 v[150:153], v149 offset:1024
	ds_read_b128 v[154:157], v149 offset:2048
	ds_read_b128 v[158:161], v149 offset:3072
	v_add_u32_e32 v149, s49, v146
	ds_read_b128 v[170:173], v149
	ds_read_b128 v[174:177], v149 offset:1024
	ds_read_b128 v[178:181], v149 offset:2048
	ds_read_b128 v[182:185], v149 offset:3072
	v_lshl_add_u64 v[228:229], s[44:45], 0, v[140:141]
	s_add_i32 m0, s78, 0xc000
	ds_read_b128 v[196:199], v148
	ds_read_b128 v[200:203], v148 offset:1024
	ds_read_b128 v[204:207], v148 offset:2048
	ds_read_b128 v[208:211], v148 offset:3072
	ds_read_b128 v[212:215], v148 offset:4096
	ds_read_b128 v[216:219], v148 offset:5120
	ds_read_b128 v[220:223], v148 offset:6144
	ds_read_b128 v[224:227], v148 offset:7168
	global_load_lds_dwordx4 v[228:229], off
	v_lshl_add_u64 v[228:229], s[44:45], 0, v[138:139]
	s_add_i32 m0, s78, 0xe000
	s_nop 0
	global_load_lds_dwordx4 v[228:229], off
	s_waitcnt vmcnt(8)
	s_waitcnt lgkmcnt(0)
	s_barrier
	v_mfma_f32_16x16x32_bf16 v[126:129], v[142:145], v[196:199], v[126:129]
	v_mfma_f32_16x16x32_bf16 v[122:125], v[154:157], v[196:199], v[122:125]
	v_mfma_f32_16x16x32_bf16 v[110:113], v[142:145], v[204:207], v[110:113]
	v_mfma_f32_16x16x32_bf16 v[106:109], v[154:157], v[204:207], v[106:109]
	v_mfma_f32_16x16x32_bf16 v[94:97], v[142:145], v[212:215], v[94:97]
	v_mfma_f32_16x16x32_bf16 v[90:93], v[154:157], v[212:215], v[90:93]
	v_mfma_f32_16x16x32_bf16 v[78:81], v[142:145], v[220:223], v[78:81]
	v_mfma_f32_16x16x32_bf16 v[74:77], v[154:157], v[220:223], v[74:77]
	v_mfma_f32_16x16x32_bf16 v[126:129], v[150:153], v[200:203], v[126:129]
	v_mfma_f32_16x16x32_bf16 v[122:125], v[158:161], v[200:203], v[122:125]
	v_mfma_f32_16x16x32_bf16 v[110:113], v[150:153], v[208:211], v[110:113]
	v_mfma_f32_16x16x32_bf16 v[106:109], v[158:161], v[208:211], v[106:109]
	v_mfma_f32_16x16x32_bf16 v[94:97], v[150:153], v[216:219], v[94:97]
	v_mfma_f32_16x16x32_bf16 v[90:93], v[158:161], v[216:219], v[90:93]
	v_mfma_f32_16x16x32_bf16 v[78:81], v[150:153], v[224:227], v[78:81]
	v_mfma_f32_16x16x32_bf16 v[74:77], v[158:161], v[224:227], v[74:77]
	v_mfma_f32_16x16x32_bf16 v[118:121], v[170:173], v[196:199], v[118:121]
	v_mfma_f32_16x16x32_bf16 v[114:117], v[178:181], v[196:199], v[114:117]
	v_mfma_f32_16x16x32_bf16 v[102:105], v[170:173], v[204:207], v[102:105]
	v_mfma_f32_16x16x32_bf16 v[98:101], v[178:181], v[204:207], v[98:101]
	v_mfma_f32_16x16x32_bf16 v[86:89], v[170:173], v[212:215], v[86:89]
	v_mfma_f32_16x16x32_bf16 v[82:85], v[178:181], v[212:215], v[82:85]
	v_mfma_f32_16x16x32_bf16 v[70:73], v[170:173], v[220:223], v[70:73]
	v_mfma_f32_16x16x32_bf16 v[66:69], v[178:181], v[220:223], v[66:69]
	v_mfma_f32_16x16x32_bf16 v[118:121], v[174:177], v[200:203], v[118:121]
	v_mfma_f32_16x16x32_bf16 v[114:117], v[182:185], v[200:203], v[114:117]
	v_mfma_f32_16x16x32_bf16 v[102:105], v[174:177], v[208:211], v[102:105]
	v_mfma_f32_16x16x32_bf16 v[98:101], v[182:185], v[208:211], v[98:101]
	v_mfma_f32_16x16x32_bf16 v[86:89], v[174:177], v[216:219], v[86:89]
	v_mfma_f32_16x16x32_bf16 v[82:85], v[182:185], v[216:219], v[82:85]
	v_mfma_f32_16x16x32_bf16 v[70:73], v[174:177], v[224:227], v[70:73]
	v_mfma_f32_16x16x32_bf16 v[66:69], v[182:185], v[224:227], v[66:69]
	s_barrier
; #define PG8_STAGE(bufoff, gbase, voff) do { _Pragma("unroll") for (int _i = 0; _i < 2; ++_i) \
;         __builtin_amdgcn_global_load_lds((const unsigned*)((const char*)(gbase) + (voff)[_i]), (PG8_LAS unsigned*)(lds + (bufoff) + ldsw + _i * 8192), 16, 0, 0); } while (0)
; #define PG8_LDA(dst, b, h) do { _Pragma("unroll") for (int m = 0; m < 4; ++m) _Pragma("unroll") for (int k = 0; k < 2; ++k) dst[m][k] = *(const PG8_LAS bf16x8*)(lds + PG8_SA(b, h) + aoff + m * 2048 + k * 1024); } while (0)
; #define PG8_LDB(dst, b, h) do { _Pragma("unroll") for (int n = 0; n < 2; ++n) _Pragma("unroll") for (int k = 0; k < 2; ++k) dst[n][k] = *(const PG8_LAS bf16x8*)(lds + PG8_SB(b, h) + boff + n * 2048 + k * 1024); } while (0)
; #define PG8_MMA(ai, bj, At, Bt) do { __builtin_amdgcn_s_setprio(1); _Pragma("unroll") for (int m = 0; m < 4; ++m) _Pragma("unroll") for (int n = 0; n < 2; ++n) _Pragma("unroll") for (int k = 0; k < 2; ++k) \
;         acc[ai][bj][m][n] = __builtin_amdgcn_mfma_f32_16x16x32_bf16(Bt[n][k], At[m][k], acc[ai][bj][m][n], 0, 0, 0); __builtin_amdgcn_s_setprio(0); } while (0)
; #define PG8_WAIT_V(n) asm volatile("s_waitcnt vmcnt(" #n ")" ::: "memory")
; #define PG8_WAIT_L(n) asm volatile("s_waitcnt lgkmcnt(" #n ")" ::: "memory")
; #define PG8_BAR __builtin_amdgcn_s_barrier()
; #define PG8_SCHED __builtin_amdgcn_sched_barrier(0)
; template <class Epi, class Sched, bool ALIGN_EPI = false, bool SP2 = false>
; __device__ __forceinline__ void gemm_phase(PG8_LAS unsigned char* lds, const Gemm g, const Sched& S, const Epi& E) {
;     ...
;             PG8_WAIT_V(8); PG8_WAIT_L(0); PG8_BAR; PG8_MMA(0, 0, At, B0); PG8_MMA(0, 1, At, B1); PG8_BAR; PG8_SCHED;
;             PG8_LDA(At, 0, 1); PG8_STAGE(PG8_SB(0, 0), b2, voffB); PG8_STAGE(PG8_SB(0, 1), b2 + hstep, voffB); PG8_STAGE(PG8_SA(0, 0), a2, voffA);
;             PG8_WAIT_V(8); PG8_WAIT_L(0); PG8_BAR; PG8_MMA(1, 0, At, B0); PG8_MMA(1, 1, At, B1); PG8_BAR; PG8_SCHED;
;             PG8_LDB(B0, 1, 0); PG8_LDB(B1, 1, 1); PG8_SCHED; PG8_LDA(At, 1, 0); PG8_STAGE(PG8_SA(0, 1), a2 + hstep, voffA);
;             PG8_WAIT_V(8); PG8_WAIT_L(0); PG8_BAR; PG8_MMA(0, 0, At, B0); PG8_MMA(0, 1, At, B1); PG8_BAR; PG8_SCHED;
	s_add_i32 s61, s61, s51
	v_lshl_add_u64 v[228:229], s[92:93], 0, v[132:133]
	s_mov_b32 m0, s61
	ds_read_b128 v[196:199], v148 offset:16384
	ds_read_b128 v[200:203], v148 offset:17408
	ds_read_b128 v[204:207], v148 offset:18432
	ds_read_b128 v[208:211], v148 offset:19456
	ds_read_b128 v[212:215], v148 offset:20480
	ds_read_b128 v[216:219], v148 offset:21504
	ds_read_b128 v[220:223], v148 offset:22528
	ds_read_b128 v[224:227], v148 offset:23552
	global_load_lds_dwordx4 v[228:229], off
	s_add_i32 m0, s61, 0x2000
	v_lshl_add_u64 v[230:231], s[92:93], 0, v[136:137]
	s_add_u32 s92, s92, s8
	s_addc_u32 s93, s93, 0
	s_add_i32 s49, s49, s51
	global_load_lds_dwordx4 v[230:231], off
	v_lshl_add_u64 v[232:233], s[92:93], 0, v[132:133]
	s_mov_b32 m0, s49
	v_lshl_add_u64 v[234:235], s[92:93], 0, v[136:137]
	global_load_lds_dwordx4 v[232:233], off
	s_add_i32 m0, s49, 0x2000
	v_lshl_add_u64 v[236:237], s[46:47], 0, v[130:131]
	global_load_lds_dwordx4 v[234:235], off
	s_mov_b32 m0, s78
	v_lshl_add_u64 v[238:239], s[46:47], 0, v[134:135]
	global_load_lds_dwordx4 v[236:237], off
	s_mov_b32 m0, s79
	s_nop 0
	global_load_lds_dwordx4 v[238:239], off
	s_waitcnt vmcnt(8)
	s_waitcnt lgkmcnt(0)
	s_barrier
	v_mfma_f32_16x16x32_bf16 v[62:65], v[142:145], v[196:199], v[62:65]
	v_mfma_f32_16x16x32_bf16 v[58:61], v[154:157], v[196:199], v[58:61]
	v_mfma_f32_16x16x32_bf16 v[46:49], v[142:145], v[204:207], v[46:49]
	v_mfma_f32_16x16x32_bf16 v[42:45], v[154:157], v[204:207], v[42:45]
	v_mfma_f32_16x16x32_bf16 v[28:31], v[142:145], v[212:215], v[28:31]
	v_mfma_f32_16x16x32_bf16 v[24:27], v[154:157], v[212:215], v[24:27]
	v_mfma_f32_16x16x32_bf16 v[12:15], v[142:145], v[220:223], v[12:15]
	v_mfma_f32_16x16x32_bf16 v[8:11], v[154:157], v[220:223], v[8:11]
	v_mfma_f32_16x16x32_bf16 v[62:65], v[150:153], v[200:203], v[62:65]
	v_mfma_f32_16x16x32_bf16 v[58:61], v[158:161], v[200:203], v[58:61]
	v_mfma_f32_16x16x32_bf16 v[46:49], v[150:153], v[208:211], v[46:49]
	v_mfma_f32_16x16x32_bf16 v[42:45], v[158:161], v[208:211], v[42:45]
	v_mfma_f32_16x16x32_bf16 v[28:31], v[150:153], v[216:219], v[28:31]
	v_mfma_f32_16x16x32_bf16 v[24:27], v[158:161], v[216:219], v[24:27]
	v_mfma_f32_16x16x32_bf16 v[12:15], v[150:153], v[224:227], v[12:15]
	v_mfma_f32_16x16x32_bf16 v[8:11], v[158:161], v[224:227], v[8:11]
	v_mfma_f32_16x16x32_bf16 v[54:57], v[170:173], v[196:199], v[54:57]
	v_mfma_f32_16x16x32_bf16 v[50:53], v[178:181], v[196:199], v[50:53]
	v_mfma_f32_16x16x32_bf16 v[38:41], v[170:173], v[204:207], v[38:41]
	v_mfma_f32_16x16x32_bf16 v[34:37], v[178:181], v[204:207], v[34:37]
	v_mfma_f32_16x16x32_bf16 v[20:23], v[170:173], v[212:215], v[20:23]
	v_mfma_f32_16x16x32_bf16 v[16:19], v[178:181], v[212:215], v[16:19]
	v_mfma_f32_16x16x32_bf16 v[4:7], v[170:173], v[220:223], v[4:7]
	v_mfma_f32_16x16x32_bf16 v[0:3], v[178:181], v[220:223], v[0:3]
	v_mfma_f32_16x16x32_bf16 v[54:57], v[174:177], v[200:203], v[54:57]
	v_mfma_f32_16x16x32_bf16 v[50:53], v[182:185], v[200:203], v[50:53]
	v_mfma_f32_16x16x32_bf16 v[38:41], v[174:177], v[208:211], v[38:41]
	v_mfma_f32_16x16x32_bf16 v[34:37], v[182:185], v[208:211], v[34:37]
	v_mfma_f32_16x16x32_bf16 v[20:23], v[174:177], v[216:219], v[20:23]
	v_mfma_f32_16x16x32_bf16 v[16:19], v[182:185], v[216:219], v[16:19]
	v_mfma_f32_16x16x32_bf16 v[4:7], v[174:177], v[224:227], v[4:7]
	v_mfma_f32_16x16x32_bf16 v[0:3], v[182:185], v[224:227], v[0:3]
	s_barrier
	s_add_i32 s49, 0, 0x18000
	v_add_u32_e32 v149, s49, v146
	s_add_i32 s61, 0, 0x1c000
	ds_read_b128 v[142:145], v149
	ds_read_b128 v[150:153], v149 offset:1024
	ds_read_b128 v[154:157], v149 offset:2048
	ds_read_b128 v[158:161], v149 offset:3072
	v_add_u32_e32 v149, s61, v146
	ds_read_b128 v[170:173], v149
	ds_read_b128 v[174:177], v149 offset:1024
	ds_read_b128 v[178:181], v149 offset:2048
	ds_read_b128 v[182:185], v149 offset:3072
	s_add_u32 s46, s46, 0x4000
	s_addc_u32 s47, s47, 0
	s_mov_b32 m0, s80
	v_lshl_add_u64 v[240:241], s[46:47], 0, v[130:131]
	ds_read_b128 v[196:199], v148 offset:32768
	ds_read_b128 v[200:203], v148 offset:33792
	ds_read_b128 v[204:207], v148 offset:34816
	ds_read_b128 v[208:211], v148 offset:35840
	ds_read_b128 v[212:215], v148 offset:36864
	ds_read_b128 v[216:219], v148 offset:37888
	ds_read_b128 v[220:223], v148 offset:38912
	ds_read_b128 v[224:227], v148 offset:39936
	global_load_lds_dwordx4 v[240:241], off
	v_lshl_add_u64 v[240:241], s[46:47], 0, v[134:135]
	s_mov_b32 m0, s81
	s_nop 0
	global_load_lds_dwordx4 v[240:241], off
	s_waitcnt vmcnt(8)
	s_waitcnt lgkmcnt(0)
	s_barrier
; #define PG8_STAGE(bufoff, gbase, voff) do { _Pragma("unroll") for (int _i = 0; _i < 2; ++_i) \
;         __builtin_amdgcn_global_load_lds((const unsigned*)((const char*)(gbase) + (voff)[_i]), (PG8_LAS unsigned*)(lds + (bufoff) + ldsw + _i * 8192), 16, 0, 0); } while (0)
; #define PG8_LDA(dst, b, h) do { _Pragma("unroll") for (int m = 0; m < 4; ++m) _Pragma("unroll") for (int k = 0; k < 2; ++k) dst[m][k] = *(const PG8_LAS bf16x8*)(lds + PG8_SA(b, h) + aoff + m * 2048 + k * 1024); } while (0)
; #define PG8_LDB(dst, b, h) do { _Pragma("unroll") for (int n = 0; n < 2; ++n) _Pragma("unroll") for (int k = 0; k < 2; ++k) dst[n][k] = *(const PG8_LAS bf16x8*)(lds + PG8_SB(b, h) + boff + n * 2048 + k * 1024); } while (0)
; #define PG8_MMA(ai, bj, At, Bt) do { __builtin_amdgcn_s_setprio(1); _Pragma("unroll") for (int m = 0; m < 4; ++m) _Pragma("unroll") for (int n = 0; n < 2; ++n) _Pragma("unroll") for (int k = 0; k < 2; ++k) \
;         acc[ai][bj][m][n] = __builtin_amdgcn_mfma_f32_16x16x32_bf16(Bt[n][k], At[m][k], acc[ai][bj][m][n], 0, 0, 0); __builtin_amdgcn_s_setprio(0); } while (0)
; #define PG8_WAIT_V(n) asm volatile("s_waitcnt vmcnt(" #n ")" ::: "memory")
; #define PG8_WAIT_L(n) asm volatile("s_waitcnt lgkmcnt(" #n ")" ::: "memory")
; #define PG8_BAR __builtin_amdgcn_s_barrier()
; #define PG8_SCHED __builtin_amdgcn_sched_barrier(0)
; template <class Epi, class Sched, bool ALIGN_EPI = false, bool SP2 = false>
; __device__ __forceinline__ void gemm_phase(PG8_LAS unsigned char* lds, const Gemm g, const Sched& S, const Epi& E) {
;     ...
;             PG8_LDB(B0, 1, 0); PG8_LDB(B1, 1, 1); PG8_SCHED; PG8_LDA(At, 1, 0); PG8_STAGE(PG8_SA(0, 1), a2 + hstep, voffA);
;             PG8_WAIT_V(8); PG8_WAIT_L(0); PG8_BAR; PG8_MMA(0, 0, At, B0); PG8_MMA(0, 1, At, B1); PG8_BAR; PG8_SCHED;
;             PG8_LDA(At, 1, 1); PG8_STAGE(PG8_SB(1, 0), b3, voffB); PG8_STAGE(PG8_SB(1, 1), b3 + hstep, voffB); PG8_STAGE(PG8_SA(1, 0), a3, voffA);
;             PG8_WAIT_V(8); PG8_WAIT_L(0); PG8_BAR; PG8_MMA(1, 0, At, B0); PG8_MMA(1, 1, At, B1); PG8_BAR; PG8_SCHED;
	v_mfma_f32_16x16x32_bf16 v[126:129], v[142:145], v[196:199], v[126:129]
	v_mfma_f32_16x16x32_bf16 v[122:125], v[154:157], v[196:199], v[122:125]
	v_mfma_f32_16x16x32_bf16 v[110:113], v[142:145], v[204:207], v[110:113]
	v_mfma_f32_16x16x32_bf16 v[106:109], v[154:157], v[204:207], v[106:109]
	v_mfma_f32_16x16x32_bf16 v[94:97], v[142:145], v[212:215], v[94:97]
	v_mfma_f32_16x16x32_bf16 v[90:93], v[154:157], v[212:215], v[90:93]
	v_mfma_f32_16x16x32_bf16 v[78:81], v[142:145], v[220:223], v[78:81]
	v_mfma_f32_16x16x32_bf16 v[74:77], v[154:157], v[220:223], v[74:77]
	v_mfma_f32_16x16x32_bf16 v[126:129], v[150:153], v[200:203], v[126:129]
	v_mfma_f32_16x16x32_bf16 v[122:125], v[158:161], v[200:203], v[122:125]
	v_mfma_f32_16x16x32_bf16 v[110:113], v[150:153], v[208:211], v[110:113]
	v_mfma_f32_16x16x32_bf16 v[106:109], v[158:161], v[208:211], v[106:109]
	v_mfma_f32_16x16x32_bf16 v[94:97], v[150:153], v[216:219], v[94:97]
	v_mfma_f32_16x16x32_bf16 v[90:93], v[158:161], v[216:219], v[90:93]
	v_mfma_f32_16x16x32_bf16 v[78:81], v[150:153], v[224:227], v[78:81]
	v_mfma_f32_16x16x32_bf16 v[74:77], v[158:161], v[224:227], v[74:77]
	v_mfma_f32_16x16x32_bf16 v[118:121], v[170:173], v[196:199], v[118:121]
	v_mfma_f32_16x16x32_bf16 v[114:117], v[178:181], v[196:199], v[114:117]
	v_mfma_f32_16x16x32_bf16 v[102:105], v[170:173], v[204:207], v[102:105]
	v_mfma_f32_16x16x32_bf16 v[98:101], v[178:181], v[204:207], v[98:101]
	v_mfma_f32_16x16x32_bf16 v[86:89], v[170:173], v[212:215], v[86:89]
	v_mfma_f32_16x16x32_bf16 v[82:85], v[178:181], v[212:215], v[82:85]
	v_mfma_f32_16x16x32_bf16 v[70:73], v[170:173], v[220:223], v[70:73]
	v_mfma_f32_16x16x32_bf16 v[66:69], v[178:181], v[220:223], v[66:69]
	v_mfma_f32_16x16x32_bf16 v[118:121], v[174:177], v[200:203], v[118:121]
	v_mfma_f32_16x16x32_bf16 v[114:117], v[182:185], v[200:203], v[114:117]
	v_mfma_f32_16x16x32_bf16 v[102:105], v[174:177], v[208:211], v[102:105]
	v_mfma_f32_16x16x32_bf16 v[98:101], v[182:185], v[208:211], v[98:101]
	v_mfma_f32_16x16x32_bf16 v[86:89], v[174:177], v[216:219], v[86:89]
	v_mfma_f32_16x16x32_bf16 v[82:85], v[182:185], v[216:219], v[82:85]
	v_mfma_f32_16x16x32_bf16 v[70:73], v[174:177], v[224:227], v[70:73]
	v_mfma_f32_16x16x32_bf16 v[66:69], v[182:185], v[224:227], v[66:69]
	s_barrier
	s_add_i32 s46, s49, s51
	v_lshl_add_u64 v[228:229], v[228:229], 0, s[34:35]
	s_mov_b32 m0, s46
	ds_read_b128 v[196:199], v148 offset:49152
	ds_read_b128 v[200:203], v148 offset:50176
	ds_read_b128 v[204:207], v148 offset:51200
	ds_read_b128 v[208:211], v148 offset:52224
	ds_read_b128 v[212:215], v148 offset:53248
	ds_read_b128 v[216:219], v148 offset:54272
	ds_read_b128 v[220:223], v148 offset:55296
	ds_read_b128 v[224:227], v148 offset:56320
	global_load_lds_dwordx4 v[228:229], off
	v_lshl_add_u64 v[228:229], v[230:231], 0, s[34:35]
	s_add_i32 m0, s46, 0x2000
	s_add_i32 s46, s61, s51
	global_load_lds_dwordx4 v[228:229], off
	v_lshl_add_u64 v[228:229], v[232:233], 0, s[34:35]
	s_mov_b32 m0, s46
	s_nop 0
	global_load_lds_dwordx4 v[228:229], off
	v_lshl_add_u64 v[228:229], v[234:235], 0, s[34:35]
	s_add_i32 m0, s46, 0x2000
	s_nop 0
	global_load_lds_dwordx4 v[228:229], off
	v_lshl_add_u64 v[228:229], v[236:237], 0, s[100:101]
	s_mov_b32 m0, s83
	s_nop 0
	global_load_lds_dwordx4 v[228:229], off
	v_lshl_add_u64 v[228:229], v[238:239], 0, s[100:101]
	s_mov_b32 m0, s84
	s_nop 0
	global_load_lds_dwordx4 v[228:229], off
	s_waitcnt vmcnt(8)
	s_waitcnt lgkmcnt(0)
	s_barrier
	v_mfma_f32_16x16x32_bf16 v[62:65], v[142:145], v[196:199], v[62:65]
	v_mfma_f32_16x16x32_bf16 v[58:61], v[154:157], v[196:199], v[58:61]
	v_mfma_f32_16x16x32_bf16 v[46:49], v[142:145], v[204:207], v[46:49]
	v_mfma_f32_16x16x32_bf16 v[42:45], v[154:157], v[204:207], v[42:45]
	v_mfma_f32_16x16x32_bf16 v[28:31], v[142:145], v[212:215], v[28:31]
	v_mfma_f32_16x16x32_bf16 v[24:27], v[154:157], v[212:215], v[24:27]
	v_mfma_f32_16x16x32_bf16 v[12:15], v[142:145], v[220:223], v[12:15]
	v_mfma_f32_16x16x32_bf16 v[8:11], v[154:157], v[220:223], v[8:11]
	v_mfma_f32_16x16x32_bf16 v[62:65], v[150:153], v[200:203], v[62:65]
	v_mfma_f32_16x16x32_bf16 v[58:61], v[158:161], v[200:203], v[58:61]
	v_mfma_f32_16x16x32_bf16 v[46:49], v[150:153], v[208:211], v[46:49]
	v_mfma_f32_16x16x32_bf16 v[42:45], v[158:161], v[208:211], v[42:45]
	v_mfma_f32_16x16x32_bf16 v[28:31], v[150:153], v[216:219], v[28:31]
	v_mfma_f32_16x16x32_bf16 v[24:27], v[158:161], v[216:219], v[24:27]
	v_mfma_f32_16x16x32_bf16 v[12:15], v[150:153], v[224:227], v[12:15]
	v_mfma_f32_16x16x32_bf16 v[8:11], v[158:161], v[224:227], v[8:11]
	v_mfma_f32_16x16x32_bf16 v[54:57], v[170:173], v[196:199], v[54:57]
	v_mfma_f32_16x16x32_bf16 v[50:53], v[178:181], v[196:199], v[50:53]
	v_mfma_f32_16x16x32_bf16 v[38:41], v[170:173], v[204:207], v[38:41]
	v_mfma_f32_16x16x32_bf16 v[34:37], v[178:181], v[204:207], v[34:37]
	v_mfma_f32_16x16x32_bf16 v[20:23], v[170:173], v[212:215], v[20:23]
	v_mfma_f32_16x16x32_bf16 v[16:19], v[178:181], v[212:215], v[16:19]
	v_mfma_f32_16x16x32_bf16 v[4:7], v[170:173], v[220:223], v[4:7]
	v_mfma_f32_16x16x32_bf16 v[0:3], v[178:181], v[220:223], v[0:3]
	v_mfma_f32_16x16x32_bf16 v[54:57], v[174:177], v[200:203], v[54:57]
	v_mfma_f32_16x16x32_bf16 v[50:53], v[182:185], v[200:203], v[50:53]
	v_mfma_f32_16x16x32_bf16 v[38:41], v[174:177], v[208:211], v[38:41]
	v_mfma_f32_16x16x32_bf16 v[34:37], v[182:185], v[208:211], v[34:37]
	v_mfma_f32_16x16x32_bf16 v[20:23], v[174:177], v[216:219], v[20:23]
	v_mfma_f32_16x16x32_bf16 v[16:19], v[182:185], v[216:219], v[16:19]
	v_mfma_f32_16x16x32_bf16 v[4:7], v[174:177], v[224:227], v[4:7]
	v_mfma_f32_16x16x32_bf16 v[0:3], v[182:185], v[224:227], v[0:3]
	s_barrier
	s_add_u32 s0, s0, 0x100
	s_addc_u32 s9, s9, 0
	s_add_u32 s44, s44, 0x10000
	s_addc_u32 s45, s45, 0
	s_cmp_ge_u32 s48, s85
	s_mov_b32 s46, s48
	s_cbranch_scc0 .LBB0_546
	s_and_b64 vcc, exec, s[40:41]
	s_cbranch_vccz .LBB0_549
	s_barrier

; __device__ __forceinline__ unsigned cvt_pk_bf16(float lo, float hi) { unsigned r; asm volatile("v_cvt_pk_bf16_f32 %0, %1, %2" : "=v"(r) : "v"(lo), "v"(hi)); return r; }
; #define GAS __attribute__((address_space(1)))
; __device__ __forceinline__ float silu_mul(float g, float u) { const float e = __builtin_amdgcn_exp2f(-1.4426950408889634f * g); return g * __builtin_amdgcn_rcpf(1.0f + e) * u; }
;     __device__ __forceinline__ void operator()(const f32x4 (&acc)[2][2][4][2], const Unit& u, int wr, int wc, int fr, int fq, const float (&pre)[8]) const {
;         const int row0 = u.pm * 256 + wr * 64 + fr, col0 = u.pn * 128 + wc * 32 + 8 * fq;
; #pragma unroll
;         for (int ai = 0; ai < 2; ++ai)
; #pragma unroll
;             for (int m = 0; m < 4; ++m) {
;                 const float rsc = pre[ai * 4 + m];
;                 const f32x4 g0 = acc[ai][0][m][0] * rsc, g1 = acc[ai][0][m][1] * rsc, u0 = acc[ai][1][m][0] * rsc, u1 = acc[ai][1][m][1] * rsc;
;                 u32x4 w; w.x = cvt_pk_bf16(silu_mul(g0[0], u0[0]), silu_mul(g0[1], u0[1])); w.y = cvt_pk_bf16(silu_mul(g0[2], u0[2]), silu_mul(g0[3], u0[3]));
;                 w.z = cvt_pk_bf16(silu_mul(g1[0], u1[0]), silu_mul(g1[1], u1[1])); w.w = cvt_pk_bf16(silu_mul(g1[2], u1[2]), silu_mul(g1[3], u1[3]));
;                 *(GAS u32x4*)(O + (size_t)(row0 + ai * 128 + m * 16) * DFF + col0) = w; }
.LBB0_583:
	v_pk_mul_f32 v[126:127], v[158:159], v[126:127] op_sel_hi:[0,1]
	v_mul_f32_e32 v153, 0xbfb8aa3b, v126
	v_exp_f32_e32 v153, v153
	v_pk_mul_f32 v[118:119], v[158:159], v[118:119] op_sel_hi:[0,1]
	v_pk_mul_f32 v[128:129], v[158:159], v[128:129] op_sel_hi:[0,1]
	v_pk_mul_f32 v[120:121], v[158:159], v[120:121] op_sel_hi:[0,1]
	v_add_f32_e32 v153, 1.0, v153
	v_rcp_f32_e32 v153, v153
	v_pk_mul_f32 v[122:123], v[158:159], v[122:123] op_sel_hi:[0,1]
	v_pk_mul_f32 v[114:115], v[158:159], v[114:115] op_sel_hi:[0,1]
	v_pk_mul_f32 v[124:125], v[158:159], v[124:125] op_sel_hi:[0,1]
	v_mul_f32_e32 v126, v126, v153
	v_mul_f32_e32 v118, v126, v118
	v_mul_f32_e32 v126, 0xbfb8aa3b, v127
	v_exp_f32_e32 v126, v126
	v_pk_mul_f32 v[116:117], v[158:159], v[116:117] op_sel_hi:[0,1]
	v_lshl_or_b32 v160, s45, 7, v147
	v_lshl_add_u32 v151, s44, 8, v33
	v_add_f32_e32 v126, 1.0, v126
	v_rcp_f32_e32 v126, v126
	v_ashrrev_i32_e32 v161, 31, v160
	v_pk_mul_f32 v[110:111], v[156:157], v[110:111] op_sel_hi:[0,1]
	v_pk_mul_f32 v[102:103], v[156:157], v[102:103] op_sel_hi:[0,1]
	v_mul_f32_e32 v126, v127, v126
	v_mul_f32_e32 v119, v126, v119
	v_cvt_pk_bf16_f32 v118, v118, v119
	v_mul_f32_e32 v119, 0xbfb8aa3b, v128
	v_exp_f32_e32 v119, v119
	v_pk_mul_f32 v[112:113], v[156:157], v[112:113] op_sel_hi:[0,1]
	v_pk_mul_f32 v[104:105], v[156:157], v[104:105] op_sel_hi:[0,1]
	v_pk_mul_f32 v[106:107], v[156:157], v[106:107] op_sel_hi:[0,1]
	v_add_f32_e32 v119, 1.0, v119
	v_rcp_f32_e32 v119, v119
	v_pk_mul_f32 v[108:109], v[156:157], v[108:109] op_sel_hi:[0,1]
	v_pk_mul_f32 v[94:95], v[154:155], v[94:95] op_sel_hi:[0,1]
	v_pk_mul_f32 v[86:87], v[154:155], v[86:87] op_sel_hi:[0,1]
	v_mul_f32_e32 v119, v128, v119
	v_mul_f32_e32 v119, v119, v120
	v_mul_f32_e32 v120, 0xbfb8aa3b, v129
	v_exp_f32_e32 v120, v120
	v_pk_mul_f32 v[96:97], v[154:155], v[96:97] op_sel_hi:[0,1]
	v_pk_mul_f32 v[88:89], v[154:155], v[88:89] op_sel_hi:[0,1]
	v_pk_mul_f32 v[90:91], v[154:155], v[90:91] op_sel_hi:[0,1]
	v_add_f32_e32 v120, 1.0, v120
	v_rcp_f32_e32 v120, v120
	v_pk_mul_f32 v[92:93], v[154:155], v[92:93] op_sel_hi:[0,1]
	v_pk_mul_f32 v[78:79], v[152:153], v[78:79] op_sel_hi:[0,1]
	v_pk_mul_f32 v[70:71], v[152:153], v[70:71] op_sel_hi:[0,1]
	v_mul_f32_e32 v120, v129, v120
	v_mul_f32_e32 v120, v120, v121
	v_cvt_pk_bf16_f32 v119, v119, v120
	v_mul_f32_e32 v120, 0xbfb8aa3b, v122
	v_exp_f32_e32 v120, v120
	v_pk_mul_f32 v[80:81], v[152:153], v[80:81] op_sel_hi:[0,1]
	v_pk_mul_f32 v[72:73], v[152:153], v[72:73] op_sel_hi:[0,1]
	v_pk_mul_f32 v[74:75], v[152:153], v[74:75] op_sel_hi:[0,1]
	v_add_f32_e32 v120, 1.0, v120
	v_rcp_f32_e32 v120, v120
	v_pk_mul_f32 v[76:77], v[152:153], v[76:77] op_sel_hi:[0,1]
	v_pk_mul_f32 v[62:63], v[150:151], v[62:63] op_sel_hi:[0,1]
	v_pk_mul_f32 v[54:55], v[150:151], v[54:55] op_sel_hi:[0,1]
	v_mul_f32_e32 v120, v122, v120
	v_mul_f32_e32 v114, v120, v114
	v_mul_f32_e32 v120, 0xbfb8aa3b, v123
	v_exp_f32_e32 v120, v120
	v_pk_mul_f32 v[64:65], v[150:151], v[64:65] op_sel_hi:[0,1]
	v_pk_mul_f32 v[56:57], v[150:151], v[56:57] op_sel_hi:[0,1]
	v_pk_mul_f32 v[58:59], v[150:151], v[58:59] op_sel_hi:[0,1]
	v_add_f32_e32 v120, 1.0, v120
	v_rcp_f32_e32 v120, v120
	v_pk_mul_f32 v[60:61], v[150:151], v[60:61] op_sel_hi:[0,1]
	v_pk_mul_f32 v[46:47], v[148:149], v[46:47] op_sel_hi:[0,1]
	v_pk_mul_f32 v[38:39], v[148:149], v[38:39] op_sel_hi:[0,1]
	v_mul_f32_e32 v120, v123, v120
	v_mul_f32_e32 v115, v120, v115
	v_cvt_pk_bf16_f32 v120, v114, v115
	v_mul_f32_e32 v114, 0xbfb8aa3b, v124
	v_mul_f32_e32 v115, 0xbfb8aa3b, v125
	v_exp_f32_e32 v114, v114
	v_exp_f32_e32 v115, v115
	v_pk_mul_f32 v[48:49], v[148:149], v[48:49] op_sel_hi:[0,1]
	v_pk_mul_f32 v[40:41], v[148:149], v[40:41] op_sel_hi:[0,1]
	v_add_f32_e32 v114, 1.0, v114
	v_add_f32_e32 v115, 1.0, v115
	v_rcp_f32_e32 v114, v114
	v_rcp_f32_e32 v115, v115
	v_pk_mul_f32 v[42:43], v[148:149], v[42:43] op_sel_hi:[0,1]
	v_pk_mul_f32 v[44:45], v[148:149], v[44:45] op_sel_hi:[0,1]
	v_mul_f32_e32 v114, v124, v114
	v_mul_f32_e32 v115, v125, v115
	v_mul_f32_e32 v114, v114, v116
	v_mul_f32_e32 v115, v115, v117
	v_cvt_pk_bf16_f32 v121, v114, v115
	s_mul_i32 s100, s44, 0x158000
	s_mul_hi_u32 s101, s44, 0x158000
	s_add_u32 s100, s64, s100
	s_addc_u32 s101, s65, s101
	v_mov_b64_e32 v[114:115], s[100:101]
	v_mad_i64_i32 v[122:123], s[44:45], v151, s34, v[114:115]
	v_lshrrev_b32_e32 v116, 6, v160
	v_and_b32_e32 v117, 63, v160
	v_lshlrev_b32_e32 v117, 1, v117
	v_lshl_or_b32 v116, v116, 15, v117
	v_mov_b32_e32 v117, 0
	v_lshl_add_u64 v[122:123], v[122:123], 0, v[116:117]
	global_store_dwordx4 v[122:123], v[118:121], off
	v_pk_mul_f32 v[28:29], v[146:147], v[28:29] op_sel_hi:[0,1]
	v_pk_mul_f32 v[20:21], v[146:147], v[20:21] op_sel_hi:[0,1]
	v_pk_mul_f32 v[118:119], v[156:157], v[100:101] op_sel_hi:[0,1]
	v_pk_mul_f32 v[100:101], v[156:157], v[98:99] op_sel_hi:[0,1]
	v_mul_f32_e32 v98, 0xbfb8aa3b, v110
	v_mul_f32_e32 v99, 0xbfb8aa3b, v111
	v_exp_f32_e32 v98, v98
	v_exp_f32_e32 v99, v99
	v_pk_mul_f32 v[30:31], v[146:147], v[30:31] op_sel_hi:[0,1]
	v_pk_mul_f32 v[22:23], v[146:147], v[22:23] op_sel_hi:[0,1]
	v_add_f32_e32 v98, 1.0, v98
	v_add_f32_e32 v99, 1.0, v99
	v_rcp_f32_e32 v98, v98
	v_rcp_f32_e32 v99, v99
	v_pk_mul_f32 v[24:25], v[146:147], v[24:25] op_sel_hi:[0,1]
	v_pk_mul_f32 v[26:27], v[146:147], v[26:27] op_sel_hi:[0,1]
	v_mul_f32_e32 v98, v110, v98
	v_mul_f32_e32 v99, v111, v99
	v_mul_f32_e32 v98, v98, v102
	v_mul_f32_e32 v99, v99, v103
	v_cvt_pk_bf16_f32 v98, v98, v99
	v_mul_f32_e32 v99, 0xbfb8aa3b, v112
	v_mul_f32_e32 v102, 0xbfb8aa3b, v113
	v_exp_f32_e32 v99, v99
	v_exp_f32_e32 v102, v102
	v_pk_mul_f32 v[12:13], v[144:145], v[12:13] op_sel_hi:[0,1]
; __device__ __forceinline__ unsigned cvt_pk_bf16(float lo, float hi) { unsigned r; asm volatile("v_cvt_pk_bf16_f32 %0, %1, %2" : "=v"(r) : "v"(lo), "v"(hi)); return r; }
; #define GAS __attribute__((address_space(1)))
; __device__ __forceinline__ float silu_mul(float g, float u) { const float e = __builtin_amdgcn_exp2f(-1.4426950408889634f * g); return g * __builtin_amdgcn_rcpf(1.0f + e) * u; }
;     __device__ __forceinline__ void operator()(const f32x4 (&acc)[2][2][4][2], const Unit& u, int wr, int wc, int fr, int fq, const float (&pre)[8]) const {
;         const int row0 = u.pm * 256 + wr * 64 + fr, col0 = u.pn * 128 + wc * 32 + 8 * fq;
; #pragma unroll
;         for (int ai = 0; ai < 2; ++ai)
; #pragma unroll
;             for (int m = 0; m < 4; ++m) {
;                 const float rsc = pre[ai * 4 + m];
;                 const f32x4 g0 = acc[ai][0][m][0] * rsc, g1 = acc[ai][0][m][1] * rsc, u0 = acc[ai][1][m][0] * rsc, u1 = acc[ai][1][m][1] * rsc;
;                 u32x4 w; w.x = cvt_pk_bf16(silu_mul(g0[0], u0[0]), silu_mul(g0[1], u0[1])); w.y = cvt_pk_bf16(silu_mul(g0[2], u0[2]), silu_mul(g0[3], u0[3]));
;                 w.z = cvt_pk_bf16(silu_mul(g1[0], u1[0]), silu_mul(g1[1], u1[1])); w.w = cvt_pk_bf16(silu_mul(g1[2], u1[2]), silu_mul(g1[3], u1[3]));
;                 *(GAS u32x4*)(O + (size_t)(row0 + ai * 128 + m * 16) * DFF + col0) = w; }
	v_pk_mul_f32 v[4:5], v[144:145], v[4:5] op_sel_hi:[0,1]
	v_add_f32_e32 v99, 1.0, v99
	v_add_f32_e32 v102, 1.0, v102
	v_rcp_f32_e32 v99, v99
	v_rcp_f32_e32 v102, v102
	v_pk_mul_f32 v[14:15], v[144:145], v[14:15] op_sel_hi:[0,1]
	v_pk_mul_f32 v[6:7], v[144:145], v[6:7] op_sel_hi:[0,1]
	v_mul_f32_e32 v99, v112, v99
	v_mul_f32_e32 v102, v113, v102
	v_mul_f32_e32 v99, v99, v104
	v_mul_f32_e32 v102, v102, v105
	v_cvt_pk_bf16_f32 v99, v99, v102
	v_mul_f32_e32 v102, 0xbfb8aa3b, v106
	v_exp_f32_e32 v102, v102
	v_pk_mul_f32 v[8:9], v[144:145], v[8:9] op_sel_hi:[0,1]
	v_pk_mul_f32 v[10:11], v[144:145], v[10:11] op_sel_hi:[0,1]
	s_andn2_b64 vcc, exec, s[42:43]
	v_add_f32_e32 v102, 1.0, v102
	v_rcp_f32_e32 v102, v102
	s_nop 0
	v_mul_f32_e32 v102, v106, v102
	v_mul_f32_e32 v100, v102, v100
	v_mul_f32_e32 v102, 0xbfb8aa3b, v107
	v_exp_f32_e32 v102, v102
	s_nop 0
	v_add_f32_e32 v102, 1.0, v102
	v_rcp_f32_e32 v102, v102
	s_nop 0
	v_mul_f32_e32 v102, v107, v102
	v_mul_f32_e32 v101, v102, v101
	v_cvt_pk_bf16_f32 v100, v100, v101
	v_mul_f32_e32 v101, 0xbfb8aa3b, v108
	v_mul_f32_e32 v102, 0xbfb8aa3b, v109
	v_exp_f32_e32 v101, v101
	v_exp_f32_e32 v102, v102
	v_add_f32_e32 v101, 1.0, v101
	v_add_f32_e32 v102, 1.0, v102
	v_rcp_f32_e32 v101, v101
	v_rcp_f32_e32 v102, v102
	v_mul_f32_e32 v101, v108, v101
	v_mul_f32_e32 v102, v109, v102
	v_mul_f32_e32 v101, v101, v118
	v_mul_f32_e32 v102, v102, v119
	v_cvt_pk_bf16_f32 v101, v101, v102
	v_or_b32_e32 v102, 16, v151
	v_mad_i64_i32 v[102:103], s[44:45], v102, s34, v[114:115]
	v_lshl_add_u64 v[102:103], v[102:103], 0, v[116:117]
	global_store_dwordx4 v[102:103], v[98:101], off
	s_nop 1
	v_pk_mul_f32 v[98:99], v[154:155], v[84:85] op_sel_hi:[0,1]
	v_pk_mul_f32 v[84:85], v[154:155], v[82:83] op_sel_hi:[0,1]
	v_mul_f32_e32 v82, 0xbfb8aa3b, v94
	v_mul_f32_e32 v83, 0xbfb8aa3b, v95
	v_exp_f32_e32 v82, v82
	v_exp_f32_e32 v83, v83
	v_add_f32_e32 v82, 1.0, v82
	v_add_f32_e32 v83, 1.0, v83
	v_rcp_f32_e32 v82, v82
	v_rcp_f32_e32 v83, v83
	v_mul_f32_e32 v82, v94, v82
	v_mul_f32_e32 v83, v95, v83
	v_mul_f32_e32 v82, v82, v86
	v_mul_f32_e32 v83, v83, v87
	v_cvt_pk_bf16_f32 v82, v82, v83
	v_mul_f32_e32 v83, 0xbfb8aa3b, v96
	v_mul_f32_e32 v86, 0xbfb8aa3b, v97
	v_exp_f32_e32 v83, v83
	v_exp_f32_e32 v86, v86
	v_add_f32_e32 v83, 1.0, v83
	v_add_f32_e32 v86, 1.0, v86
	v_rcp_f32_e32 v83, v83
	v_rcp_f32_e32 v86, v86
	v_mul_f32_e32 v83, v96, v83
	v_mul_f32_e32 v86, v97, v86
	v_mul_f32_e32 v83, v83, v88
	v_mul_f32_e32 v86, v86, v89
	v_cvt_pk_bf16_f32 v83, v83, v86
	v_mul_f32_e32 v86, 0xbfb8aa3b, v90
	v_exp_f32_e32 v86, v86
	s_nop 0
	v_add_f32_e32 v86, 1.0, v86
	v_rcp_f32_e32 v86, v86
	s_nop 0
	v_mul_f32_e32 v86, v90, v86
	v_mul_f32_e32 v84, v86, v84
	v_mul_f32_e32 v86, 0xbfb8aa3b, v91
	v_exp_f32_e32 v86, v86
	s_nop 0
	v_add_f32_e32 v86, 1.0, v86
	v_rcp_f32_e32 v86, v86
	s_nop 0
	v_mul_f32_e32 v86, v91, v86
	v_mul_f32_e32 v85, v86, v85
	v_cvt_pk_bf16_f32 v84, v84, v85
	v_mul_f32_e32 v85, 0xbfb8aa3b, v92
	v_mul_f32_e32 v86, 0xbfb8aa3b, v93
	v_exp_f32_e32 v85, v85
	v_exp_f32_e32 v86, v86
	v_add_f32_e32 v85, 1.0, v85
	v_add_f32_e32 v86, 1.0, v86
	v_rcp_f32_e32 v85, v85
	v_rcp_f32_e32 v86, v86
	v_mul_f32_e32 v85, v92, v85
	v_mul_f32_e32 v86, v93, v86
	v_mul_f32_e32 v85, v85, v98
	v_mul_f32_e32 v86, v86, v99
	v_cvt_pk_bf16_f32 v85, v85, v86
	v_or_b32_e32 v86, 32, v151
	v_mad_i64_i32 v[86:87], s[44:45], v86, s34, v[114:115]
	v_lshl_add_u64 v[86:87], v[86:87], 0, v[116:117]
	global_store_dwordx4 v[86:87], v[82:85], off
	s_nop 1
	v_pk_mul_f32 v[82:83], v[152:153], v[68:69] op_sel_hi:[0,1]
	v_pk_mul_f32 v[68:69], v[152:153], v[66:67] op_sel_hi:[0,1]
	v_mul_f32_e32 v66, 0xbfb8aa3b, v78
	v_mul_f32_e32 v67, 0xbfb8aa3b, v79
	v_exp_f32_e32 v66, v66
	v_exp_f32_e32 v67, v67
	v_add_f32_e32 v66, 1.0, v66
	v_add_f32_e32 v67, 1.0, v67
	v_rcp_f32_e32 v66, v66
	v_rcp_f32_e32 v67, v67
	v_mul_f32_e32 v66, v78, v66
	v_mul_f32_e32 v67, v79, v67
	v_mul_f32_e32 v66, v66, v70
	v_mul_f32_e32 v67, v67, v71
	v_cvt_pk_bf16_f32 v66, v66, v67
	v_mul_f32_e32 v67, 0xbfb8aa3b, v80
	v_mul_f32_e32 v70, 0xbfb8aa3b, v81
	v_exp_f32_e32 v67, v67
	v_exp_f32_e32 v70, v70
	v_add_f32_e32 v67, 1.0, v67
	v_add_f32_e32 v70, 1.0, v70
	v_rcp_f32_e32 v67, v67
	v_rcp_f32_e32 v70, v70
	v_mul_f32_e32 v67, v80, v67
	v_mul_f32_e32 v70, v81, v70
	v_mul_f32_e32 v67, v67, v72
	v_mul_f32_e32 v70, v70, v73
	v_cvt_pk_bf16_f32 v67, v67, v70
	v_mul_f32_e32 v70, 0xbfb8aa3b, v74
	v_exp_f32_e32 v70, v70
	s_nop 0
	v_add_f32_e32 v70, 1.0, v70
	v_rcp_f32_e32 v70, v70
	s_nop 0
	v_mul_f32_e32 v70, v74, v70
	v_mul_f32_e32 v68, v70, v68
	v_mul_f32_e32 v70, 0xbfb8aa3b, v75
	v_exp_f32_e32 v70, v70
	s_nop 0
	v_add_f32_e32 v70, 1.0, v70
	v_rcp_f32_e32 v70, v70
	s_nop 0
	v_mul_f32_e32 v70, v75, v70
	v_mul_f32_e32 v69, v70, v69
	v_cvt_pk_bf16_f32 v68, v68, v69
	v_mul_f32_e32 v69, 0xbfb8aa3b, v76
	v_mul_f32_e32 v70, 0xbfb8aa3b, v77
	v_exp_f32_e32 v69, v69
	v_exp_f32_e32 v70, v70
	v_add_f32_e32 v69, 1.0, v69
	v_add_f32_e32 v70, 1.0, v70
	v_rcp_f32_e32 v69, v69
	v_rcp_f32_e32 v70, v70
	v_mul_f32_e32 v69, v76, v69
	v_mul_f32_e32 v70, v77, v70
	v_mul_f32_e32 v69, v69, v82
	v_mul_f32_e32 v70, v70, v83
	v_cvt_pk_bf16_f32 v69, v69, v70
	v_or_b32_e32 v70, 48, v151
	v_mad_i64_i32 v[70:71], s[44:45], v70, s34, v[114:115]
	v_lshl_add_u64 v[70:71], v[70:71], 0, v[116:117]
	global_store_dwordx4 v[70:71], v[66:69], off
	s_nop 1
	v_pk_mul_f32 v[66:67], v[150:151], v[52:53] op_sel_hi:[0,1]
	v_pk_mul_f32 v[52:53], v[150:151], v[50:51] op_sel_hi:[0,1]
	v_mul_f32_e32 v50, 0xbfb8aa3b, v62
	v_mul_f32_e32 v51, 0xbfb8aa3b, v63
	v_exp_f32_e32 v50, v50
	v_exp_f32_e32 v51, v51
	v_add_u32_e32 v68, 0x80, v151
	v_add_f32_e32 v50, 1.0, v50
; __device__ __forceinline__ unsigned cvt_pk_bf16(float lo, float hi) { unsigned r; asm volatile("v_cvt_pk_bf16_f32 %0, %1, %2" : "=v"(r) : "v"(lo), "v"(hi)); return r; }
; #define GAS __attribute__((address_space(1)))
; __device__ __forceinline__ float silu_mul(float g, float u) { const float e = __builtin_amdgcn_exp2f(-1.4426950408889634f * g); return g * __builtin_amdgcn_rcpf(1.0f + e) * u; }
;     __device__ __forceinline__ void operator()(const f32x4 (&acc)[2][2][4][2], const Unit& u, int wr, int wc, int fr, int fq, const float (&pre)[8]) const {
;         const int row0 = u.pm * 256 + wr * 64 + fr, col0 = u.pn * 128 + wc * 32 + 8 * fq;
; #pragma unroll
;         for (int ai = 0; ai < 2; ++ai)
; #pragma unroll
;             for (int m = 0; m < 4; ++m) {
;                 const float rsc = pre[ai * 4 + m];
;                 const f32x4 g0 = acc[ai][0][m][0] * rsc, g1 = acc[ai][0][m][1] * rsc, u0 = acc[ai][1][m][0] * rsc, u1 = acc[ai][1][m][1] * rsc;
;                 u32x4 w; w.x = cvt_pk_bf16(silu_mul(g0[0], u0[0]), silu_mul(g0[1], u0[1])); w.y = cvt_pk_bf16(silu_mul(g0[2], u0[2]), silu_mul(g0[3], u0[3]));
;                 w.z = cvt_pk_bf16(silu_mul(g1[0], u1[0]), silu_mul(g1[1], u1[1])); w.w = cvt_pk_bf16(silu_mul(g1[2], u1[2]), silu_mul(g1[3], u1[3]));
;                 *(GAS u32x4*)(O + (size_t)(row0 + ai * 128 + m * 16) * DFF + col0) = w; }
	v_add_f32_e32 v51, 1.0, v51
	v_rcp_f32_e32 v50, v50
	v_rcp_f32_e32 v51, v51
	v_mul_f32_e32 v50, v62, v50
	v_mul_f32_e32 v51, v63, v51
	v_mul_f32_e32 v50, v50, v54
	v_mul_f32_e32 v51, v51, v55
	v_cvt_pk_bf16_f32 v50, v50, v51
	v_mul_f32_e32 v51, 0xbfb8aa3b, v64
	v_mul_f32_e32 v54, 0xbfb8aa3b, v65
	v_exp_f32_e32 v51, v51
	v_exp_f32_e32 v54, v54
	v_add_f32_e32 v51, 1.0, v51
	v_add_f32_e32 v54, 1.0, v54
	v_rcp_f32_e32 v51, v51
	v_rcp_f32_e32 v54, v54
	v_mul_f32_e32 v51, v64, v51
	v_mul_f32_e32 v54, v65, v54
	v_mul_f32_e32 v51, v51, v56
	v_mul_f32_e32 v54, v54, v57
	v_cvt_pk_bf16_f32 v51, v51, v54
	v_mul_f32_e32 v54, 0xbfb8aa3b, v58
	v_exp_f32_e32 v54, v54
	s_nop 0
	v_add_f32_e32 v54, 1.0, v54
	v_rcp_f32_e32 v54, v54
	s_nop 0
	v_mul_f32_e32 v54, v58, v54
	v_mul_f32_e32 v52, v54, v52
	v_mul_f32_e32 v54, 0xbfb8aa3b, v59
	v_exp_f32_e32 v54, v54
	s_nop 0
	v_add_f32_e32 v54, 1.0, v54
	v_rcp_f32_e32 v54, v54
	s_nop 0
	v_mul_f32_e32 v54, v59, v54
	v_mul_f32_e32 v53, v54, v53
	v_cvt_pk_bf16_f32 v52, v52, v53
	v_mul_f32_e32 v53, 0xbfb8aa3b, v60
	v_mul_f32_e32 v54, 0xbfb8aa3b, v61
	v_exp_f32_e32 v53, v53
	v_exp_f32_e32 v54, v54
	v_add_f32_e32 v53, 1.0, v53
	v_add_f32_e32 v54, 1.0, v54
	v_rcp_f32_e32 v53, v53
	v_rcp_f32_e32 v54, v54
	v_mul_f32_e32 v53, v60, v53
	v_mul_f32_e32 v54, v61, v54
	v_mul_f32_e32 v53, v53, v66
	v_mul_f32_e32 v54, v54, v67
	v_cvt_pk_bf16_f32 v53, v53, v54
	v_mad_i64_i32 v[54:55], s[44:45], v68, s34, v[114:115]
	v_lshl_add_u64 v[54:55], v[54:55], 0, v[116:117]
	global_store_dwordx4 v[54:55], v[50:53], off
	s_nop 1
	v_pk_mul_f32 v[50:51], v[148:149], v[36:37] op_sel_hi:[0,1]
	v_pk_mul_f32 v[36:37], v[148:149], v[34:35] op_sel_hi:[0,1]
	v_mul_f32_e32 v34, 0xbfb8aa3b, v46
	v_mul_f32_e32 v35, 0xbfb8aa3b, v47
	v_exp_f32_e32 v34, v34
	v_exp_f32_e32 v35, v35
	v_add_f32_e32 v34, 1.0, v34
	v_add_f32_e32 v35, 1.0, v35
	v_rcp_f32_e32 v34, v34
	v_rcp_f32_e32 v35, v35
	v_mul_f32_e32 v34, v46, v34
	v_mul_f32_e32 v35, v47, v35
	v_mul_f32_e32 v34, v34, v38
	v_mul_f32_e32 v35, v35, v39
	v_cvt_pk_bf16_f32 v34, v34, v35
	v_mul_f32_e32 v35, 0xbfb8aa3b, v48
	v_mul_f32_e32 v38, 0xbfb8aa3b, v49
	v_exp_f32_e32 v35, v35
	v_exp_f32_e32 v38, v38
	v_add_f32_e32 v35, 1.0, v35
	v_add_f32_e32 v38, 1.0, v38
	v_rcp_f32_e32 v35, v35
	v_rcp_f32_e32 v38, v38
	v_mul_f32_e32 v35, v48, v35
	v_mul_f32_e32 v38, v49, v38
	v_mul_f32_e32 v35, v35, v40
	v_mul_f32_e32 v38, v38, v41
	v_cvt_pk_bf16_f32 v35, v35, v38
	v_mul_f32_e32 v38, 0xbfb8aa3b, v42
	v_exp_f32_e32 v38, v38
	s_nop 0
	v_add_f32_e32 v38, 1.0, v38
	v_rcp_f32_e32 v38, v38
	s_nop 0
	v_mul_f32_e32 v38, v42, v38
	v_mul_f32_e32 v36, v38, v36
	v_mul_f32_e32 v38, 0xbfb8aa3b, v43
	v_exp_f32_e32 v38, v38
	s_nop 0
	v_add_f32_e32 v38, 1.0, v38
	v_rcp_f32_e32 v38, v38
	s_nop 0
	v_mul_f32_e32 v38, v43, v38
	v_mul_f32_e32 v37, v38, v37
	v_cvt_pk_bf16_f32 v36, v36, v37
	v_mul_f32_e32 v37, 0xbfb8aa3b, v44
	v_mul_f32_e32 v38, 0xbfb8aa3b, v45
	v_exp_f32_e32 v37, v37
	v_exp_f32_e32 v38, v38
	v_add_f32_e32 v37, 1.0, v37
	v_add_f32_e32 v38, 1.0, v38
	v_rcp_f32_e32 v37, v37
	v_rcp_f32_e32 v38, v38
	v_mul_f32_e32 v37, v44, v37
	v_mul_f32_e32 v38, v45, v38
	v_mul_f32_e32 v37, v37, v50
	v_mul_f32_e32 v38, v38, v51
	v_cvt_pk_bf16_f32 v37, v37, v38
	v_add_u32_e32 v38, 0x90, v151
	v_mad_i64_i32 v[38:39], s[44:45], v38, s34, v[114:115]
	v_lshl_add_u64 v[38:39], v[38:39], 0, v[116:117]
	global_store_dwordx4 v[38:39], v[34:37], off
	s_nop 1
	v_pk_mul_f32 v[34:35], v[146:147], v[18:19] op_sel_hi:[0,1]
	v_pk_mul_f32 v[18:19], v[146:147], v[16:17] op_sel_hi:[0,1]
	v_mul_f32_e32 v16, 0xbfb8aa3b, v28
	v_mul_f32_e32 v17, 0xbfb8aa3b, v29
	v_exp_f32_e32 v16, v16
	v_exp_f32_e32 v17, v17
	v_add_f32_e32 v16, 1.0, v16
	v_add_f32_e32 v17, 1.0, v17
	v_rcp_f32_e32 v16, v16
	v_rcp_f32_e32 v17, v17
	v_mul_f32_e32 v16, v28, v16
	v_mul_f32_e32 v17, v29, v17
	v_mul_f32_e32 v16, v16, v20
	v_mul_f32_e32 v17, v17, v21
	v_cvt_pk_bf16_f32 v16, v16, v17
	v_mul_f32_e32 v17, 0xbfb8aa3b, v30
	v_mul_f32_e32 v20, 0xbfb8aa3b, v31
	v_exp_f32_e32 v17, v17
	v_exp_f32_e32 v20, v20
	v_add_f32_e32 v17, 1.0, v17
	v_add_f32_e32 v20, 1.0, v20
	v_rcp_f32_e32 v17, v17
	v_rcp_f32_e32 v20, v20
	v_mul_f32_e32 v17, v30, v17
	v_mul_f32_e32 v20, v31, v20
	v_mul_f32_e32 v17, v17, v22
	v_mul_f32_e32 v20, v20, v23
	v_cvt_pk_bf16_f32 v17, v17, v20
	v_mul_f32_e32 v20, 0xbfb8aa3b, v24
	v_exp_f32_e32 v20, v20
	s_nop 0
	v_add_f32_e32 v20, 1.0, v20
	v_rcp_f32_e32 v20, v20
	s_nop 0
	v_mul_f32_e32 v20, v24, v20
	v_mul_f32_e32 v18, v20, v18
	v_mul_f32_e32 v20, 0xbfb8aa3b, v25
	v_exp_f32_e32 v20, v20
	s_nop 0
	v_add_f32_e32 v20, 1.0, v20
	v_rcp_f32_e32 v20, v20
	s_nop 0
	v_mul_f32_e32 v20, v25, v20
	v_mul_f32_e32 v19, v20, v19
	v_cvt_pk_bf16_f32 v18, v18, v19
	v_mul_f32_e32 v19, 0xbfb8aa3b, v26
	v_mul_f32_e32 v20, 0xbfb8aa3b, v27
	v_exp_f32_e32 v19, v19
	v_exp_f32_e32 v20, v20
	v_add_f32_e32 v19, 1.0, v19
	v_add_f32_e32 v20, 1.0, v20
	v_rcp_f32_e32 v19, v19
	v_rcp_f32_e32 v20, v20
	v_mul_f32_e32 v19, v26, v19
	v_mul_f32_e32 v20, v27, v20
	v_mul_f32_e32 v19, v19, v34
	v_mul_f32_e32 v20, v20, v35
	v_cvt_pk_bf16_f32 v19, v19, v20
	v_add_u32_e32 v20, 0xa0, v151
	v_mad_i64_i32 v[20:21], s[44:45], v20, s34, v[114:115]
	v_lshl_add_u64 v[20:21], v[20:21], 0, v[116:117]
	global_store_dwordx4 v[20:21], v[16:19], off
	s_nop 1
	v_pk_mul_f32 v[16:17], v[144:145], v[2:3] op_sel_hi:[0,1]
	v_pk_mul_f32 v[2:3], v[144:145], v[0:1] op_sel_hi:[0,1]
	v_mul_f32_e32 v0, 0xbfb8aa3b, v12
	v_mul_f32_e32 v1, 0xbfb8aa3b, v13
	v_exp_f32_e32 v0, v0
	v_exp_f32_e32 v1, v1
	v_add_f32_e32 v0, 1.0, v0
	v_add_f32_e32 v1, 1.0, v1
	v_rcp_f32_e32 v0, v0
	v_rcp_f32_e32 v1, v1
	v_mul_f32_e32 v0, v12, v0
	v_mul_f32_e32 v1, v13, v1
	v_mul_f32_e32 v0, v0, v4
	v_mul_f32_e32 v1, v1, v5
	v_cvt_pk_bf16_f32 v0, v0, v1
	v_mul_f32_e32 v1, 0xbfb8aa3b, v14
	v_mul_f32_e32 v4, 0xbfb8aa3b, v15
	v_exp_f32_e32 v1, v1
	v_exp_f32_e32 v4, v4
	v_add_f32_e32 v1, 1.0, v1
	v_add_f32_e32 v4, 1.0, v4
	v_rcp_f32_e32 v1, v1
	v_rcp_f32_e32 v4, v4
	v_mul_f32_e32 v1, v14, v1
	v_mul_f32_e32 v4, v15, v4
	v_mul_f32_e32 v1, v1, v6
	v_mul_f32_e32 v4, v4, v7
	v_cvt_pk_bf16_f32 v1, v1, v4
	v_mul_f32_e32 v4, 0xbfb8aa3b, v8
	v_exp_f32_e32 v4, v4
	s_nop 0
	v_add_f32_e32 v4, 1.0, v4
	v_rcp_f32_e32 v4, v4
	s_nop 0
	v_mul_f32_e32 v4, v8, v4
	v_mul_f32_e32 v2, v4, v2
	v_mul_f32_e32 v4, 0xbfb8aa3b, v9
	v_exp_f32_e32 v4, v4
	s_nop 0
	v_add_f32_e32 v4, 1.0, v4
	v_rcp_f32_e32 v4, v4
	s_nop 0
	v_mul_f32_e32 v4, v9, v4
	v_mul_f32_e32 v3, v4, v3
	v_cvt_pk_bf16_f32 v2, v2, v3
	v_mul_f32_e32 v3, 0xbfb8aa3b, v10
	v_mul_f32_e32 v4, 0xbfb8aa3b, v11
	v_exp_f32_e32 v3, v3
	v_exp_f32_e32 v4, v4
	v_add_f32_e32 v3, 1.0, v3
	v_add_f32_e32 v4, 1.0, v4
	v_rcp_f32_e32 v3, v3
	v_rcp_f32_e32 v4, v4
	v_mul_f32_e32 v3, v10, v3
	v_mul_f32_e32 v4, v11, v4
	v_mul_f32_e32 v3, v3, v16
	v_mul_f32_e32 v4, v4, v17
	v_cvt_pk_bf16_f32 v3, v3, v4
	v_add_u32_e32 v4, 0xb0, v151
	v_mad_i64_i32 v[4:5], s[44:45], v4, s34, v[114:115]
	v_lshl_add_u64 v[4:5], v[4:5], 0, v[116:117]
	s_mov_b64 s[44:45], -1
	global_store_dwordx4 v[4:5], v[0:3], off
	s_cbranch_vccnz .LBB0_575
; #define PG8_BAR __builtin_amdgcn_s_barrier()
; #define GAS __attribute__((address_space(1)))
; template <class Epi, class Sched, bool ALIGN_EPI = false, bool SP2 = false>
; __device__ __forceinline__ void gemm_phase(PG8_LAS unsigned char* lds, const Gemm g, const Sched& S, const Epi& E) {
;     ...
;         cur = nxt; cA = nA; cB = nB; ++ui;
;         if constexpr (Epi::PREFETCH) E.prefetch(cur, wr, fr, epre);
;         if constexpr (ALIGN_EPI) { if (wr == 1) PG8_BAR; }
;     __device__ __forceinline__ void prefetch(const Unit& u, int wr, int fr, float (&pre)[8]) const {
; #pragma unroll
;         for (int i = 0; i < 8; ++i) pre[i] = *(const GAS float*)(rs + u.pm * 256 + wr * 64 + fr + (i >> 2) * 128 + (i & 3) * 16);
;     }
	s_lshl_b32 s42, s8, 8
	s_ashr_i32 s43, s42, 31
	v_lshl_add_u64 v[0:1], s[42:43], 2, v[138:139]
	global_load_dword v158, v[0:1], off
	global_load_dword v156, v[0:1], off offset:64
	global_load_dword v154, v[0:1], off offset:128
	global_load_dword v152, v[0:1], off offset:192
	global_load_dword v150, v[0:1], off offset:512
	global_load_dword v148, v[0:1], off offset:576
	global_load_dword v146, v[0:1], off offset:640
	global_load_dword v144, v[0:1], off offset:704
	s_andn2_b64 vcc, exec, s[2:3]
	s_cbranch_vccnz .LBB0_574
	s_barrier
	s_branch .LBB0_574
